# pool_v1
# speedup vs baseline: 1.0132x; 1.0132x over previous
; __device__ __forceinline__ void unpack8(const u32x4 w, float (&f)[8]) { f[0] = bf_lo(w.x); f[1] = bf_hi(w.x); f[2] = bf_lo(w.y); f[3] = bf_hi(w.y); f[4] = bf_lo(w.z); f[5] = bf_hi(w.z); f[6] = bf_lo(w.w); f[7] = bf_hi(w.w); }
; __device__ __forceinline__ void p3_pool(const Params& p) {
;     ...
;     const int tid = threadIdx.x, cch = tid & 255, sub = tid >> 8, j0 = cch * 8;
;     const int w = 2 << (j0 >> 9);
;     float ps[8];
;     { const f32x4 a = *(const f32x4*)(p.pool_scale + j0), b = *(const f32x4*)(p.pool_scale + j0 + 4); ps[0] = a[0]; ps[1] = a[1]; ps[2] = a[2]; ps[3] = a[3]; ps[4] = b[0]; ps[5] = b[1]; ps[6] = b[2]; ps[7] = b[3]; }
;     for (int item = blockIdx.x; item < 256; item += gridDim.x) {
;         const int t0 = item * 64 + sub * 32, pos0 = t0 & (SEQ - 1);
;         float sum[8];
; #pragma unroll
;         for (int j = 0; j < 8; ++j) sum[j] = 0.f;
;         for (int i = 1; i < w; ++i) if (pos0 - i >= 0) { float f[8]; unpack8(*(const u32x4*)(proj + (size_t)(t0 - i) * NP2 + P2_U + j0), f);
; #pragma unroll
;             for (int j = 0; j < 8; ++j) sum[j] += f[j]; }
.LBB0_318:
	s_or_b64 exec, exec, s[4:5]
	v_and_b32_e32 v34, 0x7f8, v172
	s_and_b64 vcc, exec, s[0:1]
	v_mov_b32_e32 v9, 0
	s_cbranch_vccnz .LBB0_335
	v_lshlrev_b32_e32 v8, 2, v34
	global_load_dwordx4 v[0:3], v8, s[30:31]
	global_load_dwordx4 v[4:7], v8, s[30:31] offset:16
	v_lshrrev_b32_e32 v24, 9, v34
	v_lshlrev_b32_e32 v16, 1, v34
	v_readfirstlane_b32 s100, v24
	v_readfirstlane_b32 s96, v173
	v_add_u32_e32 v17, 0x2000, v16
	v_add_u32_e32 v16, 0x1000, v16
	v_sub_u32_e32 v19, 126, v24
	v_lshlrev_b32_e32 v19, 23, v19
	s_nop 3
	s_lshl_b32 s100, 2, s100
	s_add_i32 s11, s100, -1
	s_mul_i32 s22, s11, 0x3000
	s_mov_b32 s12, s2
	s_waitcnt vmcnt(0)
.Lpl_item:
	s_lshl_b32 s95, s12, 6
	s_add_i32 s95, s95, s96
	s_and_b32 s23, s95, 0x1fff
	s_mov_b32 s10, s23
	s_mul_i32 s98, s95, 0x3000
	s_add_u32 s4, s20, s98
	s_addc_u32 s5, s21, 0
	s_lshl_b32 s98, s95, 13
	s_add_u32 s8, s42, s98
	s_addc_u32 s9, s43, 0
	s_add_u32 s8, s8, 0x29600000
	s_addc_u32 s9, s9, 0
	v_mov_b32_e32 v8, 0
	v_mov_b32_e32 v9, 0
	v_mov_b32_e32 v10, 0
	v_mov_b32_e32 v11, 0
	v_mov_b32_e32 v12, 0
	v_mov_b32_e32 v13, 0
	v_mov_b32_e32 v14, 0
	v_mov_b32_e32 v15, 0
	s_min_u32 s95, s11, s23
	s_mov_b64 s[6:7], s[4:5]
	s_cmp_lt_u32 s95, 1
	s_cbranch_scc1 .Lpl_win_issued
	s_sub_u32 s6, s6, 0x3000
	s_subb_u32 s7, s7, 0
	global_load_dwordx4 v[80:83], v16, s[6:7]
	s_cmp_lt_u32 s95, 2
	s_cbranch_scc1 .Lpl_win_issued
	s_sub_u32 s6, s6, 0x3000
	s_subb_u32 s7, s7, 0
	global_load_dwordx4 v[84:87], v16, s[6:7]
	s_cmp_lt_u32 s95, 3
	s_cbranch_scc1 .Lpl_win_issued
	s_sub_u32 s6, s6, 0x3000
	s_subb_u32 s7, s7, 0
	global_load_dwordx4 v[88:91], v16, s[6:7]
	s_cmp_lt_u32 s95, 4
	s_cbranch_scc1 .Lpl_win_issued
	s_sub_u32 s6, s6, 0x3000
	s_subb_u32 s7, s7, 0
	global_load_dwordx4 v[92:95], v16, s[6:7]
	s_cmp_lt_u32 s95, 5
	s_cbranch_scc1 .Lpl_win_issued
	s_sub_u32 s6, s6, 0x3000
	s_subb_u32 s7, s7, 0
	global_load_dwordx4 v[96:99], v16, s[6:7]
	s_cmp_lt_u32 s95, 6
	s_cbranch_scc1 .Lpl_win_issued
	s_sub_u32 s6, s6, 0x3000
	s_subb_u32 s7, s7, 0
	global_load_dwordx4 v[100:103], v16, s[6:7]
	s_cmp_lt_u32 s95, 7
	s_cbranch_scc1 .Lpl_win_issued
	s_sub_u32 s6, s6, 0x3000
	s_subb_u32 s7, s7, 0
	global_load_dwordx4 v[104:107], v16, s[6:7]
	s_cmp_lt_u32 s95, 8
	s_cbranch_scc1 .Lpl_win_issued
	s_sub_u32 s6, s6, 0x3000
	s_subb_u32 s7, s7, 0
	global_load_dwordx4 v[108:111], v16, s[6:7]
	s_cmp_lt_u32 s95, 9
	s_cbranch_scc1 .Lpl_win_issued
	s_sub_u32 s6, s6, 0x3000
	s_subb_u32 s7, s7, 0
	global_load_dwordx4 v[112:115], v16, s[6:7]
	s_cmp_lt_u32 s95, 10
	s_cbranch_scc1 .Lpl_win_issued
	s_sub_u32 s6, s6, 0x3000
	s_subb_u32 s7, s7, 0
	global_load_dwordx4 v[116:119], v16, s[6:7]
	s_cmp_lt_u32 s95, 11
	s_cbranch_scc1 .Lpl_win_issued
	s_sub_u32 s6, s6, 0x3000
	s_subb_u32 s7, s7, 0
	global_load_dwordx4 v[120:123], v16, s[6:7]
	s_cmp_lt_u32 s95, 12
	s_cbranch_scc1 .Lpl_win_issued
	s_sub_u32 s6, s6, 0x3000
	s_subb_u32 s7, s7, 0
	global_load_dwordx4 v[124:127], v16, s[6:7]
	s_cmp_lt_u32 s95, 13
	s_cbranch_scc1 .Lpl_win_issued
	s_sub_u32 s6, s6, 0x3000
	s_subb_u32 s7, s7, 0
	global_load_dwordx4 v[20:23], v16, s[6:7]
	s_cmp_lt_u32 s95, 14
	s_cbranch_scc1 .Lpl_win_issued
	s_sub_u32 s6, s6, 0x3000
	s_subb_u32 s7, s7, 0
	global_load_dwordx4 v[24:27], v16, s[6:7]
	s_cmp_lt_u32 s95, 15
	s_cbranch_scc1 .Lpl_win_issued
	s_sub_u32 s6, s6, 0x3000
	s_subb_u32 s7, s7, 0
	global_load_dwordx4 v[28:31], v16, s[6:7]
.Lpl_win_issued:
	global_load_dwordx4 v[32:35], v16, s[4:5]
	global_load_dwordx4 v[36:39], v17, s[4:5]
	s_sub_u32 s6, s4, s22
	s_subb_u32 s7, s5, 0
	s_cmp_ge_u32 s10, s11
	s_cselect_b32 s6, s6, s4
	s_cselect_b32 s7, s7, s5
	global_load_dwordx4 v[40:43], v16, s[6:7]
	s_add_u32 s4, s4, 0x3000
	s_addc_u32 s5, s5, 0
	s_add_i32 s10, s10, 1
	global_load_dwordx4 v[44:47], v16, s[4:5]
	global_load_dwordx4 v[48:51], v17, s[4:5]
	s_sub_u32 s6, s4, s22
	s_subb_u32 s7, s5, 0
	s_cmp_ge_u32 s10, s11
	s_cselect_b32 s6, s6, s4
	s_cselect_b32 s7, s7, s5
	global_load_dwordx4 v[52:55], v16, s[6:7]
	s_add_u32 s4, s4, 0x3000
	s_addc_u32 s5, s5, 0
	s_add_i32 s10, s10, 1
	global_load_dwordx4 v[56:59], v16, s[4:5]
	global_load_dwordx4 v[60:63], v17, s[4:5]
	s_sub_u32 s6, s4, s22
	s_subb_u32 s7, s5, 0
	s_cmp_ge_u32 s10, s11
	s_cselect_b32 s6, s6, s4
	s_cselect_b32 s7, s7, s5
	global_load_dwordx4 v[64:67], v16, s[6:7]
	s_add_u32 s4, s4, 0x3000
	s_addc_u32 s5, s5, 0
	s_add_i32 s10, s10, 1
	global_load_dwordx4 v[68:71], v16, s[4:5]
	global_load_dwordx4 v[72:75], v17, s[4:5]
	s_sub_u32 s6, s4, s22
	s_subb_u32 s7, s5, 0
	s_cmp_ge_u32 s10, s11
	s_cselect_b32 s6, s6, s4
	s_cselect_b32 s7, s7, s5
	global_load_dwordx4 v[76:79], v16, s[6:7]
	s_add_u32 s4, s4, 0x3000
	s_addc_u32 s5, s5, 0
	s_add_i32 s10, s10, 1
	s_waitcnt vmcnt(12)
	s_cmp_lt_u32 s95, 1
	s_cbranch_scc1 .Lpl_win_done
	v_lshlrev_b32_e32 v18, 16, v80
	v_add_f32_e32 v8, v8, v18
	v_and_b32_e32 v18, 0xffff0000, v80
	v_add_f32_e32 v9, v9, v18
	v_lshlrev_b32_e32 v18, 16, v81
	v_add_f32_e32 v10, v10, v18
	v_and_b32_e32 v18, 0xffff0000, v81
	v_add_f32_e32 v11, v11, v18
	v_lshlrev_b32_e32 v18, 16, v82
	v_add_f32_e32 v12, v12, v18
	v_and_b32_e32 v18, 0xffff0000, v82
	v_add_f32_e32 v13, v13, v18
	v_lshlrev_b32_e32 v18, 16, v83
	v_add_f32_e32 v14, v14, v18
	v_and_b32_e32 v18, 0xffff0000, v83
	v_add_f32_e32 v15, v15, v18
	s_cmp_lt_u32 s95, 2
	s_cbranch_scc1 .Lpl_win_done
	v_lshlrev_b32_e32 v18, 16, v84
	v_add_f32_e32 v8, v8, v18
	v_and_b32_e32 v18, 0xffff0000, v84
	v_add_f32_e32 v9, v9, v18
	v_lshlrev_b32_e32 v18, 16, v85
	v_add_f32_e32 v10, v10, v18
	v_and_b32_e32 v18, 0xffff0000, v85
	v_add_f32_e32 v11, v11, v18
	v_lshlrev_b32_e32 v18, 16, v86
	v_add_f32_e32 v12, v12, v18
	v_and_b32_e32 v18, 0xffff0000, v86
	v_add_f32_e32 v13, v13, v18
	v_lshlrev_b32_e32 v18, 16, v87
	v_add_f32_e32 v14, v14, v18
	v_and_b32_e32 v18, 0xffff0000, v87
	v_add_f32_e32 v15, v15, v18
	s_cmp_lt_u32 s95, 3
	s_cbranch_scc1 .Lpl_win_done
; __device__ __forceinline__ void unpack8(const u32x4 w, float (&f)[8]) { f[0] = bf_lo(w.x); f[1] = bf_hi(w.x); f[2] = bf_lo(w.y); f[3] = bf_hi(w.y); f[4] = bf_lo(w.z); f[5] = bf_hi(w.z); f[6] = bf_lo(w.w); f[7] = bf_hi(w.w); }
; __device__ __forceinline__ void p3_pool(const Params& p) {
;     ...
;         for (int i = 1; i < w; ++i) if (pos0 - i >= 0) { float f[8]; unpack8(*(const u32x4*)(proj + (size_t)(t0 - i) * NP2 + P2_U + j0), f);
; #pragma unroll
;             for (int j = 0; j < 8; ++j) sum[j] += f[j]; }
	v_lshlrev_b32_e32 v18, 16, v88
	v_add_f32_e32 v8, v8, v18
	v_and_b32_e32 v18, 0xffff0000, v88
	v_add_f32_e32 v9, v9, v18
	v_lshlrev_b32_e32 v18, 16, v89
	v_add_f32_e32 v10, v10, v18
	v_and_b32_e32 v18, 0xffff0000, v89
	v_add_f32_e32 v11, v11, v18
	v_lshlrev_b32_e32 v18, 16, v90
	v_add_f32_e32 v12, v12, v18
	v_and_b32_e32 v18, 0xffff0000, v90
	v_add_f32_e32 v13, v13, v18
	v_lshlrev_b32_e32 v18, 16, v91
	v_add_f32_e32 v14, v14, v18
	v_and_b32_e32 v18, 0xffff0000, v91
	v_add_f32_e32 v15, v15, v18
	s_cmp_lt_u32 s95, 4
	s_cbranch_scc1 .Lpl_win_done
	v_lshlrev_b32_e32 v18, 16, v92
	v_add_f32_e32 v8, v8, v18
	v_and_b32_e32 v18, 0xffff0000, v92
	v_add_f32_e32 v9, v9, v18
	v_lshlrev_b32_e32 v18, 16, v93
	v_add_f32_e32 v10, v10, v18
	v_and_b32_e32 v18, 0xffff0000, v93
	v_add_f32_e32 v11, v11, v18
	v_lshlrev_b32_e32 v18, 16, v94
	v_add_f32_e32 v12, v12, v18
	v_and_b32_e32 v18, 0xffff0000, v94
	v_add_f32_e32 v13, v13, v18
	v_lshlrev_b32_e32 v18, 16, v95
	v_add_f32_e32 v14, v14, v18
	v_and_b32_e32 v18, 0xffff0000, v95
	v_add_f32_e32 v15, v15, v18
	s_cmp_lt_u32 s95, 5
	s_cbranch_scc1 .Lpl_win_done
	v_lshlrev_b32_e32 v18, 16, v96
	v_add_f32_e32 v8, v8, v18
	v_and_b32_e32 v18, 0xffff0000, v96
	v_add_f32_e32 v9, v9, v18
	v_lshlrev_b32_e32 v18, 16, v97
	v_add_f32_e32 v10, v10, v18
	v_and_b32_e32 v18, 0xffff0000, v97
	v_add_f32_e32 v11, v11, v18
	v_lshlrev_b32_e32 v18, 16, v98
	v_add_f32_e32 v12, v12, v18
	v_and_b32_e32 v18, 0xffff0000, v98
	v_add_f32_e32 v13, v13, v18
	v_lshlrev_b32_e32 v18, 16, v99
	v_add_f32_e32 v14, v14, v18
	v_and_b32_e32 v18, 0xffff0000, v99
	v_add_f32_e32 v15, v15, v18
	s_cmp_lt_u32 s95, 6
	s_cbranch_scc1 .Lpl_win_done
	v_lshlrev_b32_e32 v18, 16, v100
	v_add_f32_e32 v8, v8, v18
	v_and_b32_e32 v18, 0xffff0000, v100
	v_add_f32_e32 v9, v9, v18
	v_lshlrev_b32_e32 v18, 16, v101
	v_add_f32_e32 v10, v10, v18
	v_and_b32_e32 v18, 0xffff0000, v101
	v_add_f32_e32 v11, v11, v18
	v_lshlrev_b32_e32 v18, 16, v102
	v_add_f32_e32 v12, v12, v18
	v_and_b32_e32 v18, 0xffff0000, v102
	v_add_f32_e32 v13, v13, v18
	v_lshlrev_b32_e32 v18, 16, v103
	v_add_f32_e32 v14, v14, v18
	v_and_b32_e32 v18, 0xffff0000, v103
	v_add_f32_e32 v15, v15, v18
	s_cmp_lt_u32 s95, 7
	s_cbranch_scc1 .Lpl_win_done
	v_lshlrev_b32_e32 v18, 16, v104
	v_add_f32_e32 v8, v8, v18
	v_and_b32_e32 v18, 0xffff0000, v104
	v_add_f32_e32 v9, v9, v18
	v_lshlrev_b32_e32 v18, 16, v105
	v_add_f32_e32 v10, v10, v18
	v_and_b32_e32 v18, 0xffff0000, v105
	v_add_f32_e32 v11, v11, v18
	v_lshlrev_b32_e32 v18, 16, v106
	v_add_f32_e32 v12, v12, v18
	v_and_b32_e32 v18, 0xffff0000, v106
	v_add_f32_e32 v13, v13, v18
	v_lshlrev_b32_e32 v18, 16, v107
	v_add_f32_e32 v14, v14, v18
	v_and_b32_e32 v18, 0xffff0000, v107
	v_add_f32_e32 v15, v15, v18
	s_cmp_lt_u32 s95, 8
	s_cbranch_scc1 .Lpl_win_done
	v_lshlrev_b32_e32 v18, 16, v108
	v_add_f32_e32 v8, v8, v18
	v_and_b32_e32 v18, 0xffff0000, v108
	v_add_f32_e32 v9, v9, v18
	v_lshlrev_b32_e32 v18, 16, v109
	v_add_f32_e32 v10, v10, v18
	v_and_b32_e32 v18, 0xffff0000, v109
	v_add_f32_e32 v11, v11, v18
	v_lshlrev_b32_e32 v18, 16, v110
	v_add_f32_e32 v12, v12, v18
	v_and_b32_e32 v18, 0xffff0000, v110
	v_add_f32_e32 v13, v13, v18
	v_lshlrev_b32_e32 v18, 16, v111
	v_add_f32_e32 v14, v14, v18
	v_and_b32_e32 v18, 0xffff0000, v111
	v_add_f32_e32 v15, v15, v18
	s_cmp_lt_u32 s95, 9
	s_cbranch_scc1 .Lpl_win_done
	v_lshlrev_b32_e32 v18, 16, v112
	v_add_f32_e32 v8, v8, v18
	v_and_b32_e32 v18, 0xffff0000, v112
	v_add_f32_e32 v9, v9, v18
	v_lshlrev_b32_e32 v18, 16, v113
	v_add_f32_e32 v10, v10, v18
	v_and_b32_e32 v18, 0xffff0000, v113
	v_add_f32_e32 v11, v11, v18
	v_lshlrev_b32_e32 v18, 16, v114
	v_add_f32_e32 v12, v12, v18
	v_and_b32_e32 v18, 0xffff0000, v114
	v_add_f32_e32 v13, v13, v18
	v_lshlrev_b32_e32 v18, 16, v115
	v_add_f32_e32 v14, v14, v18
	v_and_b32_e32 v18, 0xffff0000, v115
	v_add_f32_e32 v15, v15, v18
	s_cmp_lt_u32 s95, 10
	s_cbranch_scc1 .Lpl_win_done
	v_lshlrev_b32_e32 v18, 16, v116
	v_add_f32_e32 v8, v8, v18
	v_and_b32_e32 v18, 0xffff0000, v116
	v_add_f32_e32 v9, v9, v18
	v_lshlrev_b32_e32 v18, 16, v117
	v_add_f32_e32 v10, v10, v18
	v_and_b32_e32 v18, 0xffff0000, v117
	v_add_f32_e32 v11, v11, v18
	v_lshlrev_b32_e32 v18, 16, v118
	v_add_f32_e32 v12, v12, v18
	v_and_b32_e32 v18, 0xffff0000, v118
	v_add_f32_e32 v13, v13, v18
	v_lshlrev_b32_e32 v18, 16, v119
	v_add_f32_e32 v14, v14, v18
	v_and_b32_e32 v18, 0xffff0000, v119
	v_add_f32_e32 v15, v15, v18
	s_cmp_lt_u32 s95, 11
	s_cbranch_scc1 .Lpl_win_done
	v_lshlrev_b32_e32 v18, 16, v120
	v_add_f32_e32 v8, v8, v18
	v_and_b32_e32 v18, 0xffff0000, v120
	v_add_f32_e32 v9, v9, v18
	v_lshlrev_b32_e32 v18, 16, v121
	v_add_f32_e32 v10, v10, v18
	v_and_b32_e32 v18, 0xffff0000, v121
	v_add_f32_e32 v11, v11, v18
	v_lshlrev_b32_e32 v18, 16, v122
	v_add_f32_e32 v12, v12, v18
	v_and_b32_e32 v18, 0xffff0000, v122
	v_add_f32_e32 v13, v13, v18
	v_lshlrev_b32_e32 v18, 16, v123
	v_add_f32_e32 v14, v14, v18
	v_and_b32_e32 v18, 0xffff0000, v123
	v_add_f32_e32 v15, v15, v18
	s_cmp_lt_u32 s95, 12
	s_cbranch_scc1 .Lpl_win_done
	v_lshlrev_b32_e32 v18, 16, v124
	v_add_f32_e32 v8, v8, v18
	v_and_b32_e32 v18, 0xffff0000, v124
	v_add_f32_e32 v9, v9, v18
	v_lshlrev_b32_e32 v18, 16, v125
	v_add_f32_e32 v10, v10, v18
	v_and_b32_e32 v18, 0xffff0000, v125
	v_add_f32_e32 v11, v11, v18
	v_lshlrev_b32_e32 v18, 16, v126
	v_add_f32_e32 v12, v12, v18
	v_and_b32_e32 v18, 0xffff0000, v126
	v_add_f32_e32 v13, v13, v18
	v_lshlrev_b32_e32 v18, 16, v127
	v_add_f32_e32 v14, v14, v18
	v_and_b32_e32 v18, 0xffff0000, v127
	v_add_f32_e32 v15, v15, v18
	s_cmp_lt_u32 s95, 13
	s_cbranch_scc1 .Lpl_win_done
; __device__ __forceinline__ void unpack8(const u32x4 w, float (&f)[8]) { f[0] = bf_lo(w.x); f[1] = bf_hi(w.x); f[2] = bf_lo(w.y); f[3] = bf_hi(w.y); f[4] = bf_lo(w.z); f[5] = bf_hi(w.z); f[6] = bf_lo(w.w); f[7] = bf_hi(w.w); }
; __device__ __forceinline__ void p3_pool(const Params& p) {
;     ...
;         for (int i = 1; i < w; ++i) if (pos0 - i >= 0) { float f[8]; unpack8(*(const u32x4*)(proj + (size_t)(t0 - i) * NP2 + P2_U + j0), f);
; #pragma unroll
;             for (int j = 0; j < 8; ++j) sum[j] += f[j]; }
; #pragma unroll 4
;         for (int tt = 0; tt < 32; ++tt) {
;             const int t = t0 + tt, pos = pos0 + tt;
;             float u[8], gp[8];
;             unpack8(*(const u32x4*)(proj + (size_t)t * NP2 + P2_U + j0), u);
;             unpack8(*(const u32x4*)(proj + (size_t)t * NP2 + P2_GP + j0), gp);
;             const float icnt = 1.f / (float)min(pos + 1, w);
	v_lshlrev_b32_e32 v18, 16, v20
	v_add_f32_e32 v8, v8, v18
	v_and_b32_e32 v18, 0xffff0000, v20
	v_add_f32_e32 v9, v9, v18
	v_lshlrev_b32_e32 v18, 16, v21
	v_add_f32_e32 v10, v10, v18
	v_and_b32_e32 v18, 0xffff0000, v21
	v_add_f32_e32 v11, v11, v18
	v_lshlrev_b32_e32 v18, 16, v22
	v_add_f32_e32 v12, v12, v18
	v_and_b32_e32 v18, 0xffff0000, v22
	v_add_f32_e32 v13, v13, v18
	v_lshlrev_b32_e32 v18, 16, v23
	v_add_f32_e32 v14, v14, v18
	v_and_b32_e32 v18, 0xffff0000, v23
	v_add_f32_e32 v15, v15, v18
	s_cmp_lt_u32 s95, 14
	s_cbranch_scc1 .Lpl_win_done
	v_lshlrev_b32_e32 v18, 16, v24
	v_add_f32_e32 v8, v8, v18
	v_and_b32_e32 v18, 0xffff0000, v24
	v_add_f32_e32 v9, v9, v18
	v_lshlrev_b32_e32 v18, 16, v25
	v_add_f32_e32 v10, v10, v18
	v_and_b32_e32 v18, 0xffff0000, v25
	v_add_f32_e32 v11, v11, v18
	v_lshlrev_b32_e32 v18, 16, v26
	v_add_f32_e32 v12, v12, v18
	v_and_b32_e32 v18, 0xffff0000, v26
	v_add_f32_e32 v13, v13, v18
	v_lshlrev_b32_e32 v18, 16, v27
	v_add_f32_e32 v14, v14, v18
	v_and_b32_e32 v18, 0xffff0000, v27
	v_add_f32_e32 v15, v15, v18
	s_cmp_lt_u32 s95, 15
	s_cbranch_scc1 .Lpl_win_done
	v_lshlrev_b32_e32 v18, 16, v28
	v_add_f32_e32 v8, v8, v18
	v_and_b32_e32 v18, 0xffff0000, v28
	v_add_f32_e32 v9, v9, v18
	v_lshlrev_b32_e32 v18, 16, v29
	v_add_f32_e32 v10, v10, v18
	v_and_b32_e32 v18, 0xffff0000, v29
	v_add_f32_e32 v11, v11, v18
	v_lshlrev_b32_e32 v18, 16, v30
	v_add_f32_e32 v12, v12, v18
	v_and_b32_e32 v18, 0xffff0000, v30
	v_add_f32_e32 v13, v13, v18
	v_lshlrev_b32_e32 v18, 16, v31
	v_add_f32_e32 v14, v14, v18
	v_and_b32_e32 v18, 0xffff0000, v31
	v_add_f32_e32 v15, v15, v18
.Lpl_win_done:
	s_mov_b32 s13, 0
.Lpl_pair:
	s_cmp_eq_u32 s13, 3
	s_cselect_b32 s97, 1, 0
	global_load_dwordx4 v[80:83], v16, s[4:5]
	global_load_dwordx4 v[84:87], v17, s[4:5]
	s_sub_u32 s6, s4, s22
	s_subb_u32 s7, s5, 0
	s_cmp_ge_u32 s10, s11
	s_cselect_b32 s6, s6, s4
	s_cselect_b32 s7, s7, s5
	global_load_dwordx4 v[88:91], v16, s[6:7]
	s_add_u32 s4, s4, 0x3000
	s_addc_u32 s5, s5, 0
	s_add_i32 s10, s10, 1
	global_load_dwordx4 v[92:95], v16, s[4:5]
	global_load_dwordx4 v[96:99], v17, s[4:5]
	s_sub_u32 s6, s4, s22
	s_subb_u32 s7, s5, 0
	s_cmp_ge_u32 s10, s11
	s_cselect_b32 s6, s6, s4
	s_cselect_b32 s7, s7, s5
	global_load_dwordx4 v[100:103], v16, s[6:7]
	s_add_u32 s4, s4, 0x3000
	s_addc_u32 s5, s5, 0
	s_add_i32 s10, s10, 1
	global_load_dwordx4 v[104:107], v16, s[4:5]
	global_load_dwordx4 v[108:111], v17, s[4:5]
	s_sub_u32 s6, s4, s22
	s_subb_u32 s7, s5, 0
	s_cmp_ge_u32 s10, s11
	s_cselect_b32 s6, s6, s4
	s_cselect_b32 s7, s7, s5
	global_load_dwordx4 v[112:115], v16, s[6:7]
	s_add_u32 s4, s4, 0x3000
	s_addc_u32 s5, s5, 0
	s_add_i32 s10, s10, 1
	global_load_dwordx4 v[116:119], v16, s[4:5]
	global_load_dwordx4 v[120:123], v17, s[4:5]
	s_sub_u32 s6, s4, s22
	s_subb_u32 s7, s5, 0
	s_cmp_ge_u32 s10, s11
	s_cselect_b32 s6, s6, s4
	s_cselect_b32 s7, s7, s5
	global_load_dwordx4 v[124:127], v16, s[6:7]
	s_add_u32 s4, s4, 0x3000
	s_addc_u32 s5, s5, 0
	s_add_i32 s10, s10, 1
	s_waitcnt vmcnt(21)
	s_cmp_ge_u32 s23, s11
	s_cbranch_scc1 .Lpl_fast_1
	s_add_i32 s101, s23, 1
	v_cvt_f32_u32_e32 v24, s101
	v_div_scale_f32 v25, s[6:7], v24, v24, 1.0
	v_rcp_f32_e32 v26, v25
	v_div_scale_f32 v27, vcc, 1.0, v24, 1.0
	v_fma_f32 v28, -v25, v26, 1.0
	v_fmac_f32_e32 v26, v28, v26
	v_mul_f32_e32 v28, v27, v26
	v_fma_f32 v29, -v25, v28, v27
	v_fmac_f32_e32 v28, v29, v26
	v_fma_f32 v25, -v25, v28, v27
	v_div_fmas_f32 v25, v25, v26, v28
	v_div_fixup_f32 v18, v25, v24, 1.0
	s_branch .Lpl_join_1
.Lpl_fast_1:
	v_mov_b32_e32 v18, v19
; __device__ __forceinline__ unsigned cvt_pk_bf16(float lo, float hi) { unsigned r; asm volatile("v_cvt_pk_bf16_f32 %0, %1, %2" : "=v"(r) : "v"(lo), "v"(hi)); return r; }
; __device__ __forceinline__ float silu_f(float v) { return v * __builtin_amdgcn_rcpf(1.f + __expf(-v)); }
; __device__ __forceinline__ void unpack8(const u32x4 w, float (&f)[8]) { f[0] = bf_lo(w.x); f[1] = bf_hi(w.x); f[2] = bf_lo(w.y); f[3] = bf_hi(w.y); f[4] = bf_lo(w.z); f[5] = bf_hi(w.z); f[6] = bf_lo(w.w); f[7] = bf_hi(w.w); }
; __device__ __forceinline__ void p3_pool(const Params& p) {
;     ...
;         for (int tt = 0; tt < 32; ++tt) {
;             const int t = t0 + tt, pos = pos0 + tt;
;             float u[8], gp[8];
;             unpack8(*(const u32x4*)(proj + (size_t)t * NP2 + P2_U + j0), u);
;             unpack8(*(const u32x4*)(proj + (size_t)t * NP2 + P2_GP + j0), gp);
;             const float icnt = 1.f / (float)min(pos + 1, w);
;             float y[8];
; #pragma unroll
;             for (int j = 0; j < 8; ++j) { sum[j] += u[j]; y[j] = (sum[j] * icnt - u[j]) * ps[j] * silu_f(gp[j]); }
;             u32x4 o; o.x = cvt_pk_bf16(y[0], y[1]); o.y = cvt_pk_bf16(y[2], y[3]); o.z = cvt_pk_bf16(y[4], y[5]); o.w = cvt_pk_bf16(y[6], y[7]);
;             *(u32x4*)(ycat + (size_t)t * DM + 2048 + j0) = o;
;             if (pos - (w - 1) >= 0) { float f[8]; unpack8(*(const u32x4*)(proj + (size_t)(t - (w - 1)) * NP2 + P2_U + j0), f);
; #pragma unroll
;                 for (int j = 0; j < 8; ++j) sum[j] -= f[j]; }
.Lpl_join_1:
	v_lshlrev_b32_e32 v24, 16, v32
	v_and_b32_e32 v25, 0xffff0000, v32
	v_lshlrev_b32_e32 v26, 16, v36
	v_and_b32_e32 v27, 0xffff0000, v36
	v_add_f32_e32 v8, v8, v24
	v_add_f32_e32 v9, v9, v25
	v_mul_f32_e32 v28, 0xbfb8aa3b, v26
	v_mul_f32_e32 v29, 0xbfb8aa3b, v27
	v_exp_f32_e32 v28, v28
	v_exp_f32_e32 v29, v29
	v_fma_f32 v30, v18, v8, -v24
	v_fma_f32 v31, v18, v9, -v25
	v_add_f32_e32 v28, 1.0, v28
	v_add_f32_e32 v29, 1.0, v29
	v_rcp_f32_e32 v28, v28
	v_rcp_f32_e32 v29, v29
	v_mul_f32_e32 v30, v0, v30
	v_mul_f32_e32 v31, v1, v31
	v_mul_f32_e32 v28, v28, v26
	v_mul_f32_e32 v29, v29, v27
	v_mul_f32_e32 v30, v30, v28
	v_mul_f32_e32 v31, v31, v29
	v_cvt_pk_bf16_f32 v20, v30, v31
	v_lshlrev_b32_e32 v24, 16, v33
	v_and_b32_e32 v25, 0xffff0000, v33
	v_lshlrev_b32_e32 v26, 16, v37
	v_and_b32_e32 v27, 0xffff0000, v37
	v_add_f32_e32 v10, v10, v24
	v_add_f32_e32 v11, v11, v25
	v_mul_f32_e32 v28, 0xbfb8aa3b, v26
	v_mul_f32_e32 v29, 0xbfb8aa3b, v27
	v_exp_f32_e32 v28, v28
	v_exp_f32_e32 v29, v29
	v_fma_f32 v30, v18, v10, -v24
	v_fma_f32 v31, v18, v11, -v25
	v_add_f32_e32 v28, 1.0, v28
	v_add_f32_e32 v29, 1.0, v29
	v_rcp_f32_e32 v28, v28
	v_rcp_f32_e32 v29, v29
	v_mul_f32_e32 v30, v2, v30
	v_mul_f32_e32 v31, v3, v31
	v_mul_f32_e32 v28, v28, v26
	v_mul_f32_e32 v29, v29, v27
	v_mul_f32_e32 v30, v30, v28
	v_mul_f32_e32 v31, v31, v29
	v_cvt_pk_bf16_f32 v21, v30, v31
	v_lshlrev_b32_e32 v24, 16, v34
	v_and_b32_e32 v25, 0xffff0000, v34
	v_lshlrev_b32_e32 v26, 16, v38
	v_and_b32_e32 v27, 0xffff0000, v38
	v_add_f32_e32 v12, v12, v24
	v_add_f32_e32 v13, v13, v25
	v_mul_f32_e32 v28, 0xbfb8aa3b, v26
	v_mul_f32_e32 v29, 0xbfb8aa3b, v27
	v_exp_f32_e32 v28, v28
	v_exp_f32_e32 v29, v29
	v_fma_f32 v30, v18, v12, -v24
	v_fma_f32 v31, v18, v13, -v25
	v_add_f32_e32 v28, 1.0, v28
	v_add_f32_e32 v29, 1.0, v29
	v_rcp_f32_e32 v28, v28
	v_rcp_f32_e32 v29, v29
	v_mul_f32_e32 v30, v4, v30
	v_mul_f32_e32 v31, v5, v31
	v_mul_f32_e32 v28, v28, v26
	v_mul_f32_e32 v29, v29, v27
	v_mul_f32_e32 v30, v30, v28
	v_mul_f32_e32 v31, v31, v29
	v_cvt_pk_bf16_f32 v22, v30, v31
	v_lshlrev_b32_e32 v24, 16, v35
	v_and_b32_e32 v25, 0xffff0000, v35
	v_lshlrev_b32_e32 v26, 16, v39
	v_and_b32_e32 v27, 0xffff0000, v39
	v_add_f32_e32 v14, v14, v24
	v_add_f32_e32 v15, v15, v25
	v_mul_f32_e32 v28, 0xbfb8aa3b, v26
	v_mul_f32_e32 v29, 0xbfb8aa3b, v27
	v_exp_f32_e32 v28, v28
	v_exp_f32_e32 v29, v29
	v_fma_f32 v30, v18, v14, -v24
	v_fma_f32 v31, v18, v15, -v25
	v_add_f32_e32 v28, 1.0, v28
	v_add_f32_e32 v29, 1.0, v29
	v_rcp_f32_e32 v28, v28
	v_rcp_f32_e32 v29, v29
	v_mul_f32_e32 v30, v6, v30
	v_mul_f32_e32 v31, v7, v31
	v_mul_f32_e32 v28, v28, v26
	v_mul_f32_e32 v29, v29, v27
	v_mul_f32_e32 v30, v30, v28
	v_mul_f32_e32 v31, v31, v29
	v_cvt_pk_bf16_f32 v23, v30, v31
	global_store_dwordx4 v16, v[20:23], s[8:9]
	s_add_u32 s8, s8, 0x2000
	s_addc_u32 s9, s9, 0
	s_cmp_lt_u32 s23, s11
	s_cbranch_scc1 .Lpl_nolag_1
	v_lshlrev_b32_e32 v24, 16, v40
	v_and_b32_e32 v25, 0xffff0000, v40
	v_sub_f32_e32 v8, v8, v24
	v_sub_f32_e32 v9, v9, v25
	v_lshlrev_b32_e32 v24, 16, v41
	v_and_b32_e32 v25, 0xffff0000, v41
	v_sub_f32_e32 v10, v10, v24
	v_sub_f32_e32 v11, v11, v25
	v_lshlrev_b32_e32 v24, 16, v42
	v_and_b32_e32 v25, 0xffff0000, v42
	v_sub_f32_e32 v12, v12, v24
	v_sub_f32_e32 v13, v13, v25
	v_lshlrev_b32_e32 v24, 16, v43
	v_and_b32_e32 v25, 0xffff0000, v43
	v_sub_f32_e32 v14, v14, v24
	v_sub_f32_e32 v15, v15, v25
.Lpl_nolag_1:
	s_add_i32 s23, s23, 1
	s_waitcnt vmcnt(19)
	s_cmp_ge_u32 s23, s11
	s_cbranch_scc1 .Lpl_fast_2
	s_add_i32 s101, s23, 1
	v_cvt_f32_u32_e32 v24, s101
	v_div_scale_f32 v25, s[6:7], v24, v24, 1.0
	v_rcp_f32_e32 v26, v25
	v_div_scale_f32 v27, vcc, 1.0, v24, 1.0
	v_fma_f32 v28, -v25, v26, 1.0
	v_fmac_f32_e32 v26, v28, v26
	v_mul_f32_e32 v28, v27, v26
	v_fma_f32 v29, -v25, v28, v27
	v_fmac_f32_e32 v28, v29, v26
	v_fma_f32 v25, -v25, v28, v27
	v_div_fmas_f32 v25, v25, v26, v28
	v_div_fixup_f32 v18, v25, v24, 1.0
	s_branch .Lpl_join_2

; __device__ __forceinline__ unsigned cvt_pk_bf16(float lo, float hi) { unsigned r; asm volatile("v_cvt_pk_bf16_f32 %0, %1, %2" : "=v"(r) : "v"(lo), "v"(hi)); return r; }
; __device__ __forceinline__ float silu_f(float v) { return v * __builtin_amdgcn_rcpf(1.f + __expf(-v)); }
; __device__ __forceinline__ void unpack8(const u32x4 w, float (&f)[8]) { f[0] = bf_lo(w.x); f[1] = bf_hi(w.x); f[2] = bf_lo(w.y); f[3] = bf_hi(w.y); f[4] = bf_lo(w.z); f[5] = bf_hi(w.z); f[6] = bf_lo(w.w); f[7] = bf_hi(w.w); }
; __device__ __forceinline__ void p3_pool(const Params& p) {
;     ...
;         for (int tt = 0; tt < 32; ++tt) {
;             const int t = t0 + tt, pos = pos0 + tt;
;             float u[8], gp[8];
;             unpack8(*(const u32x4*)(proj + (size_t)t * NP2 + P2_U + j0), u);
;             unpack8(*(const u32x4*)(proj + (size_t)t * NP2 + P2_GP + j0), gp);
;             const float icnt = 1.f / (float)min(pos + 1, w);
;             float y[8];
; #pragma unroll
;             for (int j = 0; j < 8; ++j) { sum[j] += u[j]; y[j] = (sum[j] * icnt - u[j]) * ps[j] * silu_f(gp[j]); }
;             u32x4 o; o.x = cvt_pk_bf16(y[0], y[1]); o.y = cvt_pk_bf16(y[2], y[3]); o.z = cvt_pk_bf16(y[4], y[5]); o.w = cvt_pk_bf16(y[6], y[7]);
;             *(u32x4*)(ycat + (size_t)t * DM + 2048 + j0) = o;
;             if (pos - (w - 1) >= 0) { float f[8]; unpack8(*(const u32x4*)(proj + (size_t)(t - (w - 1)) * NP2 + P2_U + j0), f);
; #pragma unroll
;                 for (int j = 0; j < 8; ++j) sum[j] -= f[j]; }
.Lpl_join_2:
	v_lshlrev_b32_e32 v24, 16, v44
	v_and_b32_e32 v25, 0xffff0000, v44
	v_lshlrev_b32_e32 v26, 16, v48
	v_and_b32_e32 v27, 0xffff0000, v48
	v_add_f32_e32 v8, v8, v24
	v_add_f32_e32 v9, v9, v25
	v_mul_f32_e32 v28, 0xbfb8aa3b, v26
	v_mul_f32_e32 v29, 0xbfb8aa3b, v27
	v_exp_f32_e32 v28, v28
	v_exp_f32_e32 v29, v29
	v_fma_f32 v30, v18, v8, -v24
	v_fma_f32 v31, v18, v9, -v25
	v_add_f32_e32 v28, 1.0, v28
	v_add_f32_e32 v29, 1.0, v29
	v_rcp_f32_e32 v28, v28
	v_rcp_f32_e32 v29, v29
	v_mul_f32_e32 v30, v0, v30
	v_mul_f32_e32 v31, v1, v31
	v_mul_f32_e32 v28, v28, v26
	v_mul_f32_e32 v29, v29, v27
	v_mul_f32_e32 v30, v30, v28
	v_mul_f32_e32 v31, v31, v29
	v_cvt_pk_bf16_f32 v20, v30, v31
	v_lshlrev_b32_e32 v24, 16, v45
	v_and_b32_e32 v25, 0xffff0000, v45
	v_lshlrev_b32_e32 v26, 16, v49
	v_and_b32_e32 v27, 0xffff0000, v49
	v_add_f32_e32 v10, v10, v24
	v_add_f32_e32 v11, v11, v25
	v_mul_f32_e32 v28, 0xbfb8aa3b, v26
	v_mul_f32_e32 v29, 0xbfb8aa3b, v27
	v_exp_f32_e32 v28, v28
	v_exp_f32_e32 v29, v29
	v_fma_f32 v30, v18, v10, -v24
	v_fma_f32 v31, v18, v11, -v25
	v_add_f32_e32 v28, 1.0, v28
	v_add_f32_e32 v29, 1.0, v29
	v_rcp_f32_e32 v28, v28
	v_rcp_f32_e32 v29, v29
	v_mul_f32_e32 v30, v2, v30
	v_mul_f32_e32 v31, v3, v31
	v_mul_f32_e32 v28, v28, v26
	v_mul_f32_e32 v29, v29, v27
	v_mul_f32_e32 v30, v30, v28
	v_mul_f32_e32 v31, v31, v29
	v_cvt_pk_bf16_f32 v21, v30, v31
	v_lshlrev_b32_e32 v24, 16, v46
	v_and_b32_e32 v25, 0xffff0000, v46
	v_lshlrev_b32_e32 v26, 16, v50
	v_and_b32_e32 v27, 0xffff0000, v50
	v_add_f32_e32 v12, v12, v24
	v_add_f32_e32 v13, v13, v25
	v_mul_f32_e32 v28, 0xbfb8aa3b, v26
	v_mul_f32_e32 v29, 0xbfb8aa3b, v27
	v_exp_f32_e32 v28, v28
	v_exp_f32_e32 v29, v29
	v_fma_f32 v30, v18, v12, -v24
	v_fma_f32 v31, v18, v13, -v25
	v_add_f32_e32 v28, 1.0, v28
	v_add_f32_e32 v29, 1.0, v29
	v_rcp_f32_e32 v28, v28
	v_rcp_f32_e32 v29, v29
	v_mul_f32_e32 v30, v4, v30
	v_mul_f32_e32 v31, v5, v31
	v_mul_f32_e32 v28, v28, v26
	v_mul_f32_e32 v29, v29, v27
	v_mul_f32_e32 v30, v30, v28
	v_mul_f32_e32 v31, v31, v29
	v_cvt_pk_bf16_f32 v22, v30, v31
	v_lshlrev_b32_e32 v24, 16, v47
	v_and_b32_e32 v25, 0xffff0000, v47
	v_lshlrev_b32_e32 v26, 16, v51
	v_and_b32_e32 v27, 0xffff0000, v51
	v_add_f32_e32 v14, v14, v24
	v_add_f32_e32 v15, v15, v25
	v_mul_f32_e32 v28, 0xbfb8aa3b, v26
	v_mul_f32_e32 v29, 0xbfb8aa3b, v27
	v_exp_f32_e32 v28, v28
	v_exp_f32_e32 v29, v29
	v_fma_f32 v30, v18, v14, -v24
	v_fma_f32 v31, v18, v15, -v25
	v_add_f32_e32 v28, 1.0, v28
	v_add_f32_e32 v29, 1.0, v29
	v_rcp_f32_e32 v28, v28
	v_rcp_f32_e32 v29, v29
	v_mul_f32_e32 v30, v6, v30
	v_mul_f32_e32 v31, v7, v31
	v_mul_f32_e32 v28, v28, v26
	v_mul_f32_e32 v29, v29, v27
	v_mul_f32_e32 v30, v30, v28
	v_mul_f32_e32 v31, v31, v29
	v_cvt_pk_bf16_f32 v23, v30, v31
	global_store_dwordx4 v16, v[20:23], s[8:9]
	s_add_u32 s8, s8, 0x2000
	s_addc_u32 s9, s9, 0
	s_cmp_lt_u32 s23, s11
	s_cbranch_scc1 .Lpl_nolag_2
	v_lshlrev_b32_e32 v24, 16, v52
	v_and_b32_e32 v25, 0xffff0000, v52
	v_sub_f32_e32 v8, v8, v24
	v_sub_f32_e32 v9, v9, v25
	v_lshlrev_b32_e32 v24, 16, v53
	v_and_b32_e32 v25, 0xffff0000, v53
	v_sub_f32_e32 v10, v10, v24
	v_sub_f32_e32 v11, v11, v25
	v_lshlrev_b32_e32 v24, 16, v54
	v_and_b32_e32 v25, 0xffff0000, v54
	v_sub_f32_e32 v12, v12, v24
	v_sub_f32_e32 v13, v13, v25
	v_lshlrev_b32_e32 v24, 16, v55
	v_and_b32_e32 v25, 0xffff0000, v55
	v_sub_f32_e32 v14, v14, v24
	v_sub_f32_e32 v15, v15, v25
.Lpl_nolag_2:
	s_add_i32 s23, s23, 1
	s_waitcnt vmcnt(17)
	s_cmp_ge_u32 s23, s11
	s_cbranch_scc1 .Lpl_fast_3
	s_add_i32 s101, s23, 1
	v_cvt_f32_u32_e32 v24, s101
	v_div_scale_f32 v25, s[6:7], v24, v24, 1.0
	v_rcp_f32_e32 v26, v25
	v_div_scale_f32 v27, vcc, 1.0, v24, 1.0
	v_fma_f32 v28, -v25, v26, 1.0
	v_fmac_f32_e32 v26, v28, v26
	v_mul_f32_e32 v28, v27, v26
	v_fma_f32 v29, -v25, v28, v27
	v_fmac_f32_e32 v28, v29, v26
	v_fma_f32 v25, -v25, v28, v27
	v_div_fmas_f32 v25, v25, v26, v28
	v_div_fixup_f32 v18, v25, v24, 1.0
	s_branch .Lpl_join_3

; __device__ __forceinline__ unsigned cvt_pk_bf16(float lo, float hi) { unsigned r; asm volatile("v_cvt_pk_bf16_f32 %0, %1, %2" : "=v"(r) : "v"(lo), "v"(hi)); return r; }
; __device__ __forceinline__ float silu_f(float v) { return v * __builtin_amdgcn_rcpf(1.f + __expf(-v)); }
; __device__ __forceinline__ void unpack8(const u32x4 w, float (&f)[8]) { f[0] = bf_lo(w.x); f[1] = bf_hi(w.x); f[2] = bf_lo(w.y); f[3] = bf_hi(w.y); f[4] = bf_lo(w.z); f[5] = bf_hi(w.z); f[6] = bf_lo(w.w); f[7] = bf_hi(w.w); }
; __device__ __forceinline__ void p3_pool(const Params& p) {
;     ...
;         for (int tt = 0; tt < 32; ++tt) {
;             const int t = t0 + tt, pos = pos0 + tt;
;             float u[8], gp[8];
;             unpack8(*(const u32x4*)(proj + (size_t)t * NP2 + P2_U + j0), u);
;             unpack8(*(const u32x4*)(proj + (size_t)t * NP2 + P2_GP + j0), gp);
;             const float icnt = 1.f / (float)min(pos + 1, w);
;             float y[8];
; #pragma unroll
;             for (int j = 0; j < 8; ++j) { sum[j] += u[j]; y[j] = (sum[j] * icnt - u[j]) * ps[j] * silu_f(gp[j]); }
;             u32x4 o; o.x = cvt_pk_bf16(y[0], y[1]); o.y = cvt_pk_bf16(y[2], y[3]); o.z = cvt_pk_bf16(y[4], y[5]); o.w = cvt_pk_bf16(y[6], y[7]);
;             *(u32x4*)(ycat + (size_t)t * DM + 2048 + j0) = o;
;             if (pos - (w - 1) >= 0) { float f[8]; unpack8(*(const u32x4*)(proj + (size_t)(t - (w - 1)) * NP2 + P2_U + j0), f);
; #pragma unroll
;                 for (int j = 0; j < 8; ++j) sum[j] -= f[j]; }
.Lpl_join_3:
	v_lshlrev_b32_e32 v24, 16, v56
	v_and_b32_e32 v25, 0xffff0000, v56
	v_lshlrev_b32_e32 v26, 16, v60
	v_and_b32_e32 v27, 0xffff0000, v60
	v_add_f32_e32 v8, v8, v24
	v_add_f32_e32 v9, v9, v25
	v_mul_f32_e32 v28, 0xbfb8aa3b, v26
	v_mul_f32_e32 v29, 0xbfb8aa3b, v27
	v_exp_f32_e32 v28, v28
	v_exp_f32_e32 v29, v29
	v_fma_f32 v30, v18, v8, -v24
	v_fma_f32 v31, v18, v9, -v25
	v_add_f32_e32 v28, 1.0, v28
	v_add_f32_e32 v29, 1.0, v29
	v_rcp_f32_e32 v28, v28
	v_rcp_f32_e32 v29, v29
	v_mul_f32_e32 v30, v0, v30
	v_mul_f32_e32 v31, v1, v31
	v_mul_f32_e32 v28, v28, v26
	v_mul_f32_e32 v29, v29, v27
	v_mul_f32_e32 v30, v30, v28
	v_mul_f32_e32 v31, v31, v29
	v_cvt_pk_bf16_f32 v20, v30, v31
	v_lshlrev_b32_e32 v24, 16, v57
	v_and_b32_e32 v25, 0xffff0000, v57
	v_lshlrev_b32_e32 v26, 16, v61
	v_and_b32_e32 v27, 0xffff0000, v61
	v_add_f32_e32 v10, v10, v24
	v_add_f32_e32 v11, v11, v25
	v_mul_f32_e32 v28, 0xbfb8aa3b, v26
	v_mul_f32_e32 v29, 0xbfb8aa3b, v27
	v_exp_f32_e32 v28, v28
	v_exp_f32_e32 v29, v29
	v_fma_f32 v30, v18, v10, -v24
	v_fma_f32 v31, v18, v11, -v25
	v_add_f32_e32 v28, 1.0, v28
	v_add_f32_e32 v29, 1.0, v29
	v_rcp_f32_e32 v28, v28
	v_rcp_f32_e32 v29, v29
	v_mul_f32_e32 v30, v2, v30
	v_mul_f32_e32 v31, v3, v31
	v_mul_f32_e32 v28, v28, v26
	v_mul_f32_e32 v29, v29, v27
	v_mul_f32_e32 v30, v30, v28
	v_mul_f32_e32 v31, v31, v29
	v_cvt_pk_bf16_f32 v21, v30, v31
	v_lshlrev_b32_e32 v24, 16, v58
	v_and_b32_e32 v25, 0xffff0000, v58
	v_lshlrev_b32_e32 v26, 16, v62
	v_and_b32_e32 v27, 0xffff0000, v62
	v_add_f32_e32 v12, v12, v24
	v_add_f32_e32 v13, v13, v25
	v_mul_f32_e32 v28, 0xbfb8aa3b, v26
	v_mul_f32_e32 v29, 0xbfb8aa3b, v27
	v_exp_f32_e32 v28, v28
	v_exp_f32_e32 v29, v29
	v_fma_f32 v30, v18, v12, -v24
	v_fma_f32 v31, v18, v13, -v25
	v_add_f32_e32 v28, 1.0, v28
	v_add_f32_e32 v29, 1.0, v29
	v_rcp_f32_e32 v28, v28
	v_rcp_f32_e32 v29, v29
	v_mul_f32_e32 v30, v4, v30
	v_mul_f32_e32 v31, v5, v31
	v_mul_f32_e32 v28, v28, v26
	v_mul_f32_e32 v29, v29, v27
	v_mul_f32_e32 v30, v30, v28
	v_mul_f32_e32 v31, v31, v29
	v_cvt_pk_bf16_f32 v22, v30, v31
	v_lshlrev_b32_e32 v24, 16, v59
	v_and_b32_e32 v25, 0xffff0000, v59
	v_lshlrev_b32_e32 v26, 16, v63
	v_and_b32_e32 v27, 0xffff0000, v63
	v_add_f32_e32 v14, v14, v24
	v_add_f32_e32 v15, v15, v25
	v_mul_f32_e32 v28, 0xbfb8aa3b, v26
	v_mul_f32_e32 v29, 0xbfb8aa3b, v27
	v_exp_f32_e32 v28, v28
	v_exp_f32_e32 v29, v29
	v_fma_f32 v30, v18, v14, -v24
	v_fma_f32 v31, v18, v15, -v25
	v_add_f32_e32 v28, 1.0, v28
	v_add_f32_e32 v29, 1.0, v29
	v_rcp_f32_e32 v28, v28
	v_rcp_f32_e32 v29, v29
	v_mul_f32_e32 v30, v6, v30
	v_mul_f32_e32 v31, v7, v31
	v_mul_f32_e32 v28, v28, v26
	v_mul_f32_e32 v29, v29, v27
	v_mul_f32_e32 v30, v30, v28
	v_mul_f32_e32 v31, v31, v29
	v_cvt_pk_bf16_f32 v23, v30, v31
	global_store_dwordx4 v16, v[20:23], s[8:9]
	s_add_u32 s8, s8, 0x2000
	s_addc_u32 s9, s9, 0
	s_cmp_lt_u32 s23, s11
	s_cbranch_scc1 .Lpl_nolag_3
	v_lshlrev_b32_e32 v24, 16, v64
	v_and_b32_e32 v25, 0xffff0000, v64
	v_sub_f32_e32 v8, v8, v24
	v_sub_f32_e32 v9, v9, v25
	v_lshlrev_b32_e32 v24, 16, v65
	v_and_b32_e32 v25, 0xffff0000, v65
	v_sub_f32_e32 v10, v10, v24
	v_sub_f32_e32 v11, v11, v25
	v_lshlrev_b32_e32 v24, 16, v66
	v_and_b32_e32 v25, 0xffff0000, v66
	v_sub_f32_e32 v12, v12, v24
	v_sub_f32_e32 v13, v13, v25
	v_lshlrev_b32_e32 v24, 16, v67
	v_and_b32_e32 v25, 0xffff0000, v67
	v_sub_f32_e32 v14, v14, v24
	v_sub_f32_e32 v15, v15, v25
.Lpl_nolag_3:
	s_add_i32 s23, s23, 1
	s_waitcnt vmcnt(15)
	s_cmp_ge_u32 s23, s11
	s_cbranch_scc1 .Lpl_fast_4
	s_add_i32 s101, s23, 1
	v_cvt_f32_u32_e32 v24, s101
	v_div_scale_f32 v25, s[6:7], v24, v24, 1.0
	v_rcp_f32_e32 v26, v25
	v_div_scale_f32 v27, vcc, 1.0, v24, 1.0
	v_fma_f32 v28, -v25, v26, 1.0
	v_fmac_f32_e32 v26, v28, v26
	v_mul_f32_e32 v28, v27, v26
	v_fma_f32 v29, -v25, v28, v27
	v_fmac_f32_e32 v28, v29, v26
	v_fma_f32 v25, -v25, v28, v27
	v_div_fmas_f32 v25, v25, v26, v28
	v_div_fixup_f32 v18, v25, v24, 1.0
	s_branch .Lpl_join_4

; __device__ __forceinline__ unsigned cvt_pk_bf16(float lo, float hi) { unsigned r; asm volatile("v_cvt_pk_bf16_f32 %0, %1, %2" : "=v"(r) : "v"(lo), "v"(hi)); return r; }
; __device__ __forceinline__ float silu_f(float v) { return v * __builtin_amdgcn_rcpf(1.f + __expf(-v)); }
; __device__ __forceinline__ void unpack8(const u32x4 w, float (&f)[8]) { f[0] = bf_lo(w.x); f[1] = bf_hi(w.x); f[2] = bf_lo(w.y); f[3] = bf_hi(w.y); f[4] = bf_lo(w.z); f[5] = bf_hi(w.z); f[6] = bf_lo(w.w); f[7] = bf_hi(w.w); }
; __device__ __forceinline__ void p3_pool(const Params& p) {
;     ...
;         for (int tt = 0; tt < 32; ++tt) {
;             const int t = t0 + tt, pos = pos0 + tt;
;             float u[8], gp[8];
;             unpack8(*(const u32x4*)(proj + (size_t)t * NP2 + P2_U + j0), u);
;             unpack8(*(const u32x4*)(proj + (size_t)t * NP2 + P2_GP + j0), gp);
;             const float icnt = 1.f / (float)min(pos + 1, w);
;             float y[8];
; #pragma unroll
;             for (int j = 0; j < 8; ++j) { sum[j] += u[j]; y[j] = (sum[j] * icnt - u[j]) * ps[j] * silu_f(gp[j]); }
;             u32x4 o; o.x = cvt_pk_bf16(y[0], y[1]); o.y = cvt_pk_bf16(y[2], y[3]); o.z = cvt_pk_bf16(y[4], y[5]); o.w = cvt_pk_bf16(y[6], y[7]);
;             *(u32x4*)(ycat + (size_t)t * DM + 2048 + j0) = o;
;             if (pos - (w - 1) >= 0) { float f[8]; unpack8(*(const u32x4*)(proj + (size_t)(t - (w - 1)) * NP2 + P2_U + j0), f);
; #pragma unroll
;                 for (int j = 0; j < 8; ++j) sum[j] -= f[j]; }
.Lpl_join_4:
	v_lshlrev_b32_e32 v24, 16, v68
	v_and_b32_e32 v25, 0xffff0000, v68
	v_lshlrev_b32_e32 v26, 16, v72
	v_and_b32_e32 v27, 0xffff0000, v72
	v_add_f32_e32 v8, v8, v24
	v_add_f32_e32 v9, v9, v25
	v_mul_f32_e32 v28, 0xbfb8aa3b, v26
	v_mul_f32_e32 v29, 0xbfb8aa3b, v27
	v_exp_f32_e32 v28, v28
	v_exp_f32_e32 v29, v29
	v_fma_f32 v30, v18, v8, -v24
	v_fma_f32 v31, v18, v9, -v25
	v_add_f32_e32 v28, 1.0, v28
	v_add_f32_e32 v29, 1.0, v29
	v_rcp_f32_e32 v28, v28
	v_rcp_f32_e32 v29, v29
	v_mul_f32_e32 v30, v0, v30
	v_mul_f32_e32 v31, v1, v31
	v_mul_f32_e32 v28, v28, v26
	v_mul_f32_e32 v29, v29, v27
	v_mul_f32_e32 v30, v30, v28
	v_mul_f32_e32 v31, v31, v29
	v_cvt_pk_bf16_f32 v20, v30, v31
	v_lshlrev_b32_e32 v24, 16, v69
	v_and_b32_e32 v25, 0xffff0000, v69
	v_lshlrev_b32_e32 v26, 16, v73
	v_and_b32_e32 v27, 0xffff0000, v73
	v_add_f32_e32 v10, v10, v24
	v_add_f32_e32 v11, v11, v25
	v_mul_f32_e32 v28, 0xbfb8aa3b, v26
	v_mul_f32_e32 v29, 0xbfb8aa3b, v27
	v_exp_f32_e32 v28, v28
	v_exp_f32_e32 v29, v29
	v_fma_f32 v30, v18, v10, -v24
	v_fma_f32 v31, v18, v11, -v25
	v_add_f32_e32 v28, 1.0, v28
	v_add_f32_e32 v29, 1.0, v29
	v_rcp_f32_e32 v28, v28
	v_rcp_f32_e32 v29, v29
	v_mul_f32_e32 v30, v2, v30
	v_mul_f32_e32 v31, v3, v31
	v_mul_f32_e32 v28, v28, v26
	v_mul_f32_e32 v29, v29, v27
	v_mul_f32_e32 v30, v30, v28
	v_mul_f32_e32 v31, v31, v29
	v_cvt_pk_bf16_f32 v21, v30, v31
	v_lshlrev_b32_e32 v24, 16, v70
	v_and_b32_e32 v25, 0xffff0000, v70
	v_lshlrev_b32_e32 v26, 16, v74
	v_and_b32_e32 v27, 0xffff0000, v74
	v_add_f32_e32 v12, v12, v24
	v_add_f32_e32 v13, v13, v25
	v_mul_f32_e32 v28, 0xbfb8aa3b, v26
	v_mul_f32_e32 v29, 0xbfb8aa3b, v27
	v_exp_f32_e32 v28, v28
	v_exp_f32_e32 v29, v29
	v_fma_f32 v30, v18, v12, -v24
	v_fma_f32 v31, v18, v13, -v25
	v_add_f32_e32 v28, 1.0, v28
	v_add_f32_e32 v29, 1.0, v29
	v_rcp_f32_e32 v28, v28
	v_rcp_f32_e32 v29, v29
	v_mul_f32_e32 v30, v4, v30
	v_mul_f32_e32 v31, v5, v31
	v_mul_f32_e32 v28, v28, v26
	v_mul_f32_e32 v29, v29, v27
	v_mul_f32_e32 v30, v30, v28
	v_mul_f32_e32 v31, v31, v29
	v_cvt_pk_bf16_f32 v22, v30, v31
	v_lshlrev_b32_e32 v24, 16, v71
	v_and_b32_e32 v25, 0xffff0000, v71
	v_lshlrev_b32_e32 v26, 16, v75
	v_and_b32_e32 v27, 0xffff0000, v75
	v_add_f32_e32 v14, v14, v24
	v_add_f32_e32 v15, v15, v25
	v_mul_f32_e32 v28, 0xbfb8aa3b, v26
	v_mul_f32_e32 v29, 0xbfb8aa3b, v27
	v_exp_f32_e32 v28, v28
	v_exp_f32_e32 v29, v29
	v_fma_f32 v30, v18, v14, -v24
	v_fma_f32 v31, v18, v15, -v25
	v_add_f32_e32 v28, 1.0, v28
	v_add_f32_e32 v29, 1.0, v29
	v_rcp_f32_e32 v28, v28
	v_rcp_f32_e32 v29, v29
	v_mul_f32_e32 v30, v6, v30
	v_mul_f32_e32 v31, v7, v31
	v_mul_f32_e32 v28, v28, v26
	v_mul_f32_e32 v29, v29, v27
	v_mul_f32_e32 v30, v30, v28
	v_mul_f32_e32 v31, v31, v29
	v_cvt_pk_bf16_f32 v23, v30, v31
	global_store_dwordx4 v16, v[20:23], s[8:9]
	s_add_u32 s8, s8, 0x2000
	s_addc_u32 s9, s9, 0
	s_cmp_lt_u32 s23, s11
	s_cbranch_scc1 .Lpl_nolag_4
	v_lshlrev_b32_e32 v24, 16, v76
	v_and_b32_e32 v25, 0xffff0000, v76
	v_sub_f32_e32 v8, v8, v24
	v_sub_f32_e32 v9, v9, v25
	v_lshlrev_b32_e32 v24, 16, v77
	v_and_b32_e32 v25, 0xffff0000, v77
	v_sub_f32_e32 v10, v10, v24
	v_sub_f32_e32 v11, v11, v25
	v_lshlrev_b32_e32 v24, 16, v78
	v_and_b32_e32 v25, 0xffff0000, v78
	v_sub_f32_e32 v12, v12, v24
	v_sub_f32_e32 v13, v13, v25
	v_lshlrev_b32_e32 v24, 16, v79
	v_and_b32_e32 v25, 0xffff0000, v79
	v_sub_f32_e32 v14, v14, v24
	v_sub_f32_e32 v15, v15, v25
.Lpl_nolag_4:
	s_add_i32 s23, s23, 1
	s_cmp_eq_u32 s97, 1
	s_cbranch_scc1 .Lpl_skip_issue
	global_load_dwordx4 v[32:35], v16, s[4:5]
	global_load_dwordx4 v[36:39], v17, s[4:5]
	s_sub_u32 s6, s4, s22
	s_subb_u32 s7, s5, 0
	s_cmp_ge_u32 s10, s11
	s_cselect_b32 s6, s6, s4
	s_cselect_b32 s7, s7, s5
	global_load_dwordx4 v[40:43], v16, s[6:7]
	s_add_u32 s4, s4, 0x3000
	s_addc_u32 s5, s5, 0
	s_add_i32 s10, s10, 1
	global_load_dwordx4 v[44:47], v16, s[4:5]
	global_load_dwordx4 v[48:51], v17, s[4:5]
	s_sub_u32 s6, s4, s22
	s_subb_u32 s7, s5, 0
	s_cmp_ge_u32 s10, s11
	s_cselect_b32 s6, s6, s4
	s_cselect_b32 s7, s7, s5
	global_load_dwordx4 v[52:55], v16, s[6:7]
	s_add_u32 s4, s4, 0x3000
	s_addc_u32 s5, s5, 0
	s_add_i32 s10, s10, 1
	global_load_dwordx4 v[56:59], v16, s[4:5]
	global_load_dwordx4 v[60:63], v17, s[4:5]
	s_sub_u32 s6, s4, s22
	s_subb_u32 s7, s5, 0
	s_cmp_ge_u32 s10, s11
	s_cselect_b32 s6, s6, s4
	s_cselect_b32 s7, s7, s5
	global_load_dwordx4 v[64:67], v16, s[6:7]
	s_add_u32 s4, s4, 0x3000
	s_addc_u32 s5, s5, 0
	s_add_i32 s10, s10, 1
	global_load_dwordx4 v[68:71], v16, s[4:5]
	global_load_dwordx4 v[72:75], v17, s[4:5]
	s_sub_u32 s6, s4, s22
	s_subb_u32 s7, s5, 0
	s_cmp_ge_u32 s10, s11
	s_cselect_b32 s6, s6, s4
	s_cselect_b32 s7, s7, s5
	global_load_dwordx4 v[76:79], v16, s[6:7]
	s_add_u32 s4, s4, 0x3000
	s_addc_u32 s5, s5, 0
	s_add_i32 s10, s10, 1
.Lpl_skip_issue:
	s_cmp_eq_u32 s97, 1
	s_cbranch_scc1 .Lpl_wl_5
	s_waitcnt vmcnt(25)
	s_branch .Lpl_wj_5
.Lpl_wl_5:
	s_waitcnt vmcnt(13)
.Lpl_wj_5:
	s_cmp_ge_u32 s23, s11
	s_cbranch_scc1 .Lpl_fast_5
	s_add_i32 s101, s23, 1
	v_cvt_f32_u32_e32 v24, s101
	v_div_scale_f32 v25, s[6:7], v24, v24, 1.0
	v_rcp_f32_e32 v26, v25
	v_div_scale_f32 v27, vcc, 1.0, v24, 1.0
	v_fma_f32 v28, -v25, v26, 1.0
	v_fmac_f32_e32 v26, v28, v26
	v_mul_f32_e32 v28, v27, v26
	v_fma_f32 v29, -v25, v28, v27
	v_fmac_f32_e32 v28, v29, v26
	v_fma_f32 v25, -v25, v28, v27
	v_div_fmas_f32 v25, v25, v26, v28
	v_div_fixup_f32 v18, v25, v24, 1.0
	s_branch .Lpl_join_5

; __device__ __forceinline__ unsigned cvt_pk_bf16(float lo, float hi) { unsigned r; asm volatile("v_cvt_pk_bf16_f32 %0, %1, %2" : "=v"(r) : "v"(lo), "v"(hi)); return r; }
; __device__ __forceinline__ float silu_f(float v) { return v * __builtin_amdgcn_rcpf(1.f + __expf(-v)); }
; __device__ __forceinline__ void unpack8(const u32x4 w, float (&f)[8]) { f[0] = bf_lo(w.x); f[1] = bf_hi(w.x); f[2] = bf_lo(w.y); f[3] = bf_hi(w.y); f[4] = bf_lo(w.z); f[5] = bf_hi(w.z); f[6] = bf_lo(w.w); f[7] = bf_hi(w.w); }
; __device__ __forceinline__ void p3_pool(const Params& p) {
;     ...
;         for (int tt = 0; tt < 32; ++tt) {
;             const int t = t0 + tt, pos = pos0 + tt;
;             float u[8], gp[8];
;             unpack8(*(const u32x4*)(proj + (size_t)t * NP2 + P2_U + j0), u);
;             unpack8(*(const u32x4*)(proj + (size_t)t * NP2 + P2_GP + j0), gp);
;             const float icnt = 1.f / (float)min(pos + 1, w);
;             float y[8];
; #pragma unroll
;             for (int j = 0; j < 8; ++j) { sum[j] += u[j]; y[j] = (sum[j] * icnt - u[j]) * ps[j] * silu_f(gp[j]); }
;             u32x4 o; o.x = cvt_pk_bf16(y[0], y[1]); o.y = cvt_pk_bf16(y[2], y[3]); o.z = cvt_pk_bf16(y[4], y[5]); o.w = cvt_pk_bf16(y[6], y[7]);
;             *(u32x4*)(ycat + (size_t)t * DM + 2048 + j0) = o;
;             if (pos - (w - 1) >= 0) { float f[8]; unpack8(*(const u32x4*)(proj + (size_t)(t - (w - 1)) * NP2 + P2_U + j0), f);
; #pragma unroll
;                 for (int j = 0; j < 8; ++j) sum[j] -= f[j]; }
.Lpl_join_5:
	v_lshlrev_b32_e32 v24, 16, v80
	v_and_b32_e32 v25, 0xffff0000, v80
	v_lshlrev_b32_e32 v26, 16, v84
	v_and_b32_e32 v27, 0xffff0000, v84
	v_add_f32_e32 v8, v8, v24
	v_add_f32_e32 v9, v9, v25
	v_mul_f32_e32 v28, 0xbfb8aa3b, v26
	v_mul_f32_e32 v29, 0xbfb8aa3b, v27
	v_exp_f32_e32 v28, v28
	v_exp_f32_e32 v29, v29
	v_fma_f32 v30, v18, v8, -v24
	v_fma_f32 v31, v18, v9, -v25
	v_add_f32_e32 v28, 1.0, v28
	v_add_f32_e32 v29, 1.0, v29
	v_rcp_f32_e32 v28, v28
	v_rcp_f32_e32 v29, v29
	v_mul_f32_e32 v30, v0, v30
	v_mul_f32_e32 v31, v1, v31
	v_mul_f32_e32 v28, v28, v26
	v_mul_f32_e32 v29, v29, v27
	v_mul_f32_e32 v30, v30, v28
	v_mul_f32_e32 v31, v31, v29
	v_cvt_pk_bf16_f32 v20, v30, v31
	v_lshlrev_b32_e32 v24, 16, v81
	v_and_b32_e32 v25, 0xffff0000, v81
	v_lshlrev_b32_e32 v26, 16, v85
	v_and_b32_e32 v27, 0xffff0000, v85
	v_add_f32_e32 v10, v10, v24
	v_add_f32_e32 v11, v11, v25
	v_mul_f32_e32 v28, 0xbfb8aa3b, v26
	v_mul_f32_e32 v29, 0xbfb8aa3b, v27
	v_exp_f32_e32 v28, v28
	v_exp_f32_e32 v29, v29
	v_fma_f32 v30, v18, v10, -v24
	v_fma_f32 v31, v18, v11, -v25
	v_add_f32_e32 v28, 1.0, v28
	v_add_f32_e32 v29, 1.0, v29
	v_rcp_f32_e32 v28, v28
	v_rcp_f32_e32 v29, v29
	v_mul_f32_e32 v30, v2, v30
	v_mul_f32_e32 v31, v3, v31
	v_mul_f32_e32 v28, v28, v26
	v_mul_f32_e32 v29, v29, v27
	v_mul_f32_e32 v30, v30, v28
	v_mul_f32_e32 v31, v31, v29
	v_cvt_pk_bf16_f32 v21, v30, v31
	v_lshlrev_b32_e32 v24, 16, v82
	v_and_b32_e32 v25, 0xffff0000, v82
	v_lshlrev_b32_e32 v26, 16, v86
	v_and_b32_e32 v27, 0xffff0000, v86
	v_add_f32_e32 v12, v12, v24
	v_add_f32_e32 v13, v13, v25
	v_mul_f32_e32 v28, 0xbfb8aa3b, v26
	v_mul_f32_e32 v29, 0xbfb8aa3b, v27
	v_exp_f32_e32 v28, v28
	v_exp_f32_e32 v29, v29
	v_fma_f32 v30, v18, v12, -v24
	v_fma_f32 v31, v18, v13, -v25
	v_add_f32_e32 v28, 1.0, v28
	v_add_f32_e32 v29, 1.0, v29
	v_rcp_f32_e32 v28, v28
	v_rcp_f32_e32 v29, v29
	v_mul_f32_e32 v30, v4, v30
	v_mul_f32_e32 v31, v5, v31
	v_mul_f32_e32 v28, v28, v26
	v_mul_f32_e32 v29, v29, v27
	v_mul_f32_e32 v30, v30, v28
	v_mul_f32_e32 v31, v31, v29
	v_cvt_pk_bf16_f32 v22, v30, v31
	v_lshlrev_b32_e32 v24, 16, v83
	v_and_b32_e32 v25, 0xffff0000, v83
	v_lshlrev_b32_e32 v26, 16, v87
	v_and_b32_e32 v27, 0xffff0000, v87
	v_add_f32_e32 v14, v14, v24
	v_add_f32_e32 v15, v15, v25
	v_mul_f32_e32 v28, 0xbfb8aa3b, v26
	v_mul_f32_e32 v29, 0xbfb8aa3b, v27
	v_exp_f32_e32 v28, v28
	v_exp_f32_e32 v29, v29
	v_fma_f32 v30, v18, v14, -v24
	v_fma_f32 v31, v18, v15, -v25
	v_add_f32_e32 v28, 1.0, v28
	v_add_f32_e32 v29, 1.0, v29
	v_rcp_f32_e32 v28, v28
	v_rcp_f32_e32 v29, v29
	v_mul_f32_e32 v30, v6, v30
	v_mul_f32_e32 v31, v7, v31
	v_mul_f32_e32 v28, v28, v26
	v_mul_f32_e32 v29, v29, v27
	v_mul_f32_e32 v30, v30, v28
	v_mul_f32_e32 v31, v31, v29
	v_cvt_pk_bf16_f32 v23, v30, v31
	global_store_dwordx4 v16, v[20:23], s[8:9]
	s_add_u32 s8, s8, 0x2000
	s_addc_u32 s9, s9, 0
	s_cmp_lt_u32 s23, s11
	s_cbranch_scc1 .Lpl_nolag_5
	v_lshlrev_b32_e32 v24, 16, v88
	v_and_b32_e32 v25, 0xffff0000, v88
	v_sub_f32_e32 v8, v8, v24
	v_sub_f32_e32 v9, v9, v25
	v_lshlrev_b32_e32 v24, 16, v89
	v_and_b32_e32 v25, 0xffff0000, v89
	v_sub_f32_e32 v10, v10, v24
	v_sub_f32_e32 v11, v11, v25
	v_lshlrev_b32_e32 v24, 16, v90
	v_and_b32_e32 v25, 0xffff0000, v90
	v_sub_f32_e32 v12, v12, v24
	v_sub_f32_e32 v13, v13, v25
	v_lshlrev_b32_e32 v24, 16, v91
	v_and_b32_e32 v25, 0xffff0000, v91
	v_sub_f32_e32 v14, v14, v24
	v_sub_f32_e32 v15, v15, v25
.Lpl_nolag_5:
	s_add_i32 s23, s23, 1
	s_cmp_eq_u32 s97, 1
	s_cbranch_scc1 .Lpl_wl_6
	s_waitcnt vmcnt(23)
	s_branch .Lpl_wj_6
.Lpl_wl_6:
	s_waitcnt vmcnt(11)

; __device__ __forceinline__ unsigned cvt_pk_bf16(float lo, float hi) { unsigned r; asm volatile("v_cvt_pk_bf16_f32 %0, %1, %2" : "=v"(r) : "v"(lo), "v"(hi)); return r; }
; __device__ __forceinline__ float silu_f(float v) { return v * __builtin_amdgcn_rcpf(1.f + __expf(-v)); }
; __device__ __forceinline__ void unpack8(const u32x4 w, float (&f)[8]) { f[0] = bf_lo(w.x); f[1] = bf_hi(w.x); f[2] = bf_lo(w.y); f[3] = bf_hi(w.y); f[4] = bf_lo(w.z); f[5] = bf_hi(w.z); f[6] = bf_lo(w.w); f[7] = bf_hi(w.w); }
; __device__ __forceinline__ void p3_pool(const Params& p) {
;     ...
;         for (int tt = 0; tt < 32; ++tt) {
;             const int t = t0 + tt, pos = pos0 + tt;
;             float u[8], gp[8];
;             unpack8(*(const u32x4*)(proj + (size_t)t * NP2 + P2_U + j0), u);
;             unpack8(*(const u32x4*)(proj + (size_t)t * NP2 + P2_GP + j0), gp);
;             const float icnt = 1.f / (float)min(pos + 1, w);
;             float y[8];
; #pragma unroll
;             for (int j = 0; j < 8; ++j) { sum[j] += u[j]; y[j] = (sum[j] * icnt - u[j]) * ps[j] * silu_f(gp[j]); }
;             u32x4 o; o.x = cvt_pk_bf16(y[0], y[1]); o.y = cvt_pk_bf16(y[2], y[3]); o.z = cvt_pk_bf16(y[4], y[5]); o.w = cvt_pk_bf16(y[6], y[7]);
;             *(u32x4*)(ycat + (size_t)t * DM + 2048 + j0) = o;
;             if (pos - (w - 1) >= 0) { float f[8]; unpack8(*(const u32x4*)(proj + (size_t)(t - (w - 1)) * NP2 + P2_U + j0), f);
; #pragma unroll
;                 for (int j = 0; j < 8; ++j) sum[j] -= f[j]; }
.Lpl_join_6:
	v_lshlrev_b32_e32 v24, 16, v92
	v_and_b32_e32 v25, 0xffff0000, v92
	v_lshlrev_b32_e32 v26, 16, v96
	v_and_b32_e32 v27, 0xffff0000, v96
	v_add_f32_e32 v8, v8, v24
	v_add_f32_e32 v9, v9, v25
	v_mul_f32_e32 v28, 0xbfb8aa3b, v26
	v_mul_f32_e32 v29, 0xbfb8aa3b, v27
	v_exp_f32_e32 v28, v28
	v_exp_f32_e32 v29, v29
	v_fma_f32 v30, v18, v8, -v24
	v_fma_f32 v31, v18, v9, -v25
	v_add_f32_e32 v28, 1.0, v28
	v_add_f32_e32 v29, 1.0, v29
	v_rcp_f32_e32 v28, v28
	v_rcp_f32_e32 v29, v29
	v_mul_f32_e32 v30, v0, v30
	v_mul_f32_e32 v31, v1, v31
	v_mul_f32_e32 v28, v28, v26
	v_mul_f32_e32 v29, v29, v27
	v_mul_f32_e32 v30, v30, v28
	v_mul_f32_e32 v31, v31, v29
	v_cvt_pk_bf16_f32 v20, v30, v31
	v_lshlrev_b32_e32 v24, 16, v93
	v_and_b32_e32 v25, 0xffff0000, v93
	v_lshlrev_b32_e32 v26, 16, v97
	v_and_b32_e32 v27, 0xffff0000, v97
	v_add_f32_e32 v10, v10, v24
	v_add_f32_e32 v11, v11, v25
	v_mul_f32_e32 v28, 0xbfb8aa3b, v26
	v_mul_f32_e32 v29, 0xbfb8aa3b, v27
	v_exp_f32_e32 v28, v28
	v_exp_f32_e32 v29, v29
	v_fma_f32 v30, v18, v10, -v24
	v_fma_f32 v31, v18, v11, -v25
	v_add_f32_e32 v28, 1.0, v28
	v_add_f32_e32 v29, 1.0, v29
	v_rcp_f32_e32 v28, v28
	v_rcp_f32_e32 v29, v29
	v_mul_f32_e32 v30, v2, v30
	v_mul_f32_e32 v31, v3, v31
	v_mul_f32_e32 v28, v28, v26
	v_mul_f32_e32 v29, v29, v27
	v_mul_f32_e32 v30, v30, v28
	v_mul_f32_e32 v31, v31, v29
	v_cvt_pk_bf16_f32 v21, v30, v31
	v_lshlrev_b32_e32 v24, 16, v94
	v_and_b32_e32 v25, 0xffff0000, v94
	v_lshlrev_b32_e32 v26, 16, v98
	v_and_b32_e32 v27, 0xffff0000, v98
	v_add_f32_e32 v12, v12, v24
	v_add_f32_e32 v13, v13, v25
	v_mul_f32_e32 v28, 0xbfb8aa3b, v26
	v_mul_f32_e32 v29, 0xbfb8aa3b, v27
	v_exp_f32_e32 v28, v28
	v_exp_f32_e32 v29, v29
	v_fma_f32 v30, v18, v12, -v24
	v_fma_f32 v31, v18, v13, -v25
	v_add_f32_e32 v28, 1.0, v28
	v_add_f32_e32 v29, 1.0, v29
	v_rcp_f32_e32 v28, v28
	v_rcp_f32_e32 v29, v29
	v_mul_f32_e32 v30, v4, v30
	v_mul_f32_e32 v31, v5, v31
	v_mul_f32_e32 v28, v28, v26
	v_mul_f32_e32 v29, v29, v27
	v_mul_f32_e32 v30, v30, v28
	v_mul_f32_e32 v31, v31, v29
	v_cvt_pk_bf16_f32 v22, v30, v31
	v_lshlrev_b32_e32 v24, 16, v95
	v_and_b32_e32 v25, 0xffff0000, v95
	v_lshlrev_b32_e32 v26, 16, v99
	v_and_b32_e32 v27, 0xffff0000, v99
	v_add_f32_e32 v14, v14, v24
	v_add_f32_e32 v15, v15, v25
	v_mul_f32_e32 v28, 0xbfb8aa3b, v26
	v_mul_f32_e32 v29, 0xbfb8aa3b, v27
	v_exp_f32_e32 v28, v28
	v_exp_f32_e32 v29, v29
	v_fma_f32 v30, v18, v14, -v24
	v_fma_f32 v31, v18, v15, -v25
	v_add_f32_e32 v28, 1.0, v28
	v_add_f32_e32 v29, 1.0, v29
	v_rcp_f32_e32 v28, v28
	v_rcp_f32_e32 v29, v29
	v_mul_f32_e32 v30, v6, v30
	v_mul_f32_e32 v31, v7, v31
	v_mul_f32_e32 v28, v28, v26
	v_mul_f32_e32 v29, v29, v27
	v_mul_f32_e32 v30, v30, v28
	v_mul_f32_e32 v31, v31, v29
	v_cvt_pk_bf16_f32 v23, v30, v31
	global_store_dwordx4 v16, v[20:23], s[8:9]
	s_add_u32 s8, s8, 0x2000
	s_addc_u32 s9, s9, 0
	s_cmp_lt_u32 s23, s11
	s_cbranch_scc1 .Lpl_nolag_6
	v_lshlrev_b32_e32 v24, 16, v100
	v_and_b32_e32 v25, 0xffff0000, v100
	v_sub_f32_e32 v8, v8, v24
	v_sub_f32_e32 v9, v9, v25
	v_lshlrev_b32_e32 v24, 16, v101
	v_and_b32_e32 v25, 0xffff0000, v101
	v_sub_f32_e32 v10, v10, v24
	v_sub_f32_e32 v11, v11, v25
	v_lshlrev_b32_e32 v24, 16, v102
	v_and_b32_e32 v25, 0xffff0000, v102
	v_sub_f32_e32 v12, v12, v24
	v_sub_f32_e32 v13, v13, v25
	v_lshlrev_b32_e32 v24, 16, v103
	v_and_b32_e32 v25, 0xffff0000, v103
	v_sub_f32_e32 v14, v14, v24
	v_sub_f32_e32 v15, v15, v25
.Lpl_nolag_6:
	s_add_i32 s23, s23, 1
	s_cmp_eq_u32 s97, 1
	s_cbranch_scc1 .Lpl_wl_7
	s_waitcnt vmcnt(21)
	s_branch .Lpl_wj_7
.Lpl_wl_7:
	s_waitcnt vmcnt(9)

; __device__ __forceinline__ unsigned cvt_pk_bf16(float lo, float hi) { unsigned r; asm volatile("v_cvt_pk_bf16_f32 %0, %1, %2" : "=v"(r) : "v"(lo), "v"(hi)); return r; }
; __device__ __forceinline__ float silu_f(float v) { return v * __builtin_amdgcn_rcpf(1.f + __expf(-v)); }
; __device__ __forceinline__ void unpack8(const u32x4 w, float (&f)[8]) { f[0] = bf_lo(w.x); f[1] = bf_hi(w.x); f[2] = bf_lo(w.y); f[3] = bf_hi(w.y); f[4] = bf_lo(w.z); f[5] = bf_hi(w.z); f[6] = bf_lo(w.w); f[7] = bf_hi(w.w); }
; __device__ __forceinline__ void p3_pool(const Params& p) {
;     ...
;         for (int tt = 0; tt < 32; ++tt) {
;             const int t = t0 + tt, pos = pos0 + tt;
;             float u[8], gp[8];
;             unpack8(*(const u32x4*)(proj + (size_t)t * NP2 + P2_U + j0), u);
;             unpack8(*(const u32x4*)(proj + (size_t)t * NP2 + P2_GP + j0), gp);
;             const float icnt = 1.f / (float)min(pos + 1, w);
;             float y[8];
; #pragma unroll
;             for (int j = 0; j < 8; ++j) { sum[j] += u[j]; y[j] = (sum[j] * icnt - u[j]) * ps[j] * silu_f(gp[j]); }
;             u32x4 o; o.x = cvt_pk_bf16(y[0], y[1]); o.y = cvt_pk_bf16(y[2], y[3]); o.z = cvt_pk_bf16(y[4], y[5]); o.w = cvt_pk_bf16(y[6], y[7]);
;             *(u32x4*)(ycat + (size_t)t * DM + 2048 + j0) = o;
;             if (pos - (w - 1) >= 0) { float f[8]; unpack8(*(const u32x4*)(proj + (size_t)(t - (w - 1)) * NP2 + P2_U + j0), f);
; #pragma unroll
;                 for (int j = 0; j < 8; ++j) sum[j] -= f[j]; }
.Lpl_join_7:
	v_lshlrev_b32_e32 v24, 16, v104
	v_and_b32_e32 v25, 0xffff0000, v104
	v_lshlrev_b32_e32 v26, 16, v108
	v_and_b32_e32 v27, 0xffff0000, v108
	v_add_f32_e32 v8, v8, v24
	v_add_f32_e32 v9, v9, v25
	v_mul_f32_e32 v28, 0xbfb8aa3b, v26
	v_mul_f32_e32 v29, 0xbfb8aa3b, v27
	v_exp_f32_e32 v28, v28
	v_exp_f32_e32 v29, v29
	v_fma_f32 v30, v18, v8, -v24
	v_fma_f32 v31, v18, v9, -v25
	v_add_f32_e32 v28, 1.0, v28
	v_add_f32_e32 v29, 1.0, v29
	v_rcp_f32_e32 v28, v28
	v_rcp_f32_e32 v29, v29
	v_mul_f32_e32 v30, v0, v30
	v_mul_f32_e32 v31, v1, v31
	v_mul_f32_e32 v28, v28, v26
	v_mul_f32_e32 v29, v29, v27
	v_mul_f32_e32 v30, v30, v28
	v_mul_f32_e32 v31, v31, v29
	v_cvt_pk_bf16_f32 v20, v30, v31
	v_lshlrev_b32_e32 v24, 16, v105
	v_and_b32_e32 v25, 0xffff0000, v105
	v_lshlrev_b32_e32 v26, 16, v109
	v_and_b32_e32 v27, 0xffff0000, v109
	v_add_f32_e32 v10, v10, v24
	v_add_f32_e32 v11, v11, v25
	v_mul_f32_e32 v28, 0xbfb8aa3b, v26
	v_mul_f32_e32 v29, 0xbfb8aa3b, v27
	v_exp_f32_e32 v28, v28
	v_exp_f32_e32 v29, v29
	v_fma_f32 v30, v18, v10, -v24
	v_fma_f32 v31, v18, v11, -v25
	v_add_f32_e32 v28, 1.0, v28
	v_add_f32_e32 v29, 1.0, v29
	v_rcp_f32_e32 v28, v28
	v_rcp_f32_e32 v29, v29
	v_mul_f32_e32 v30, v2, v30
	v_mul_f32_e32 v31, v3, v31
	v_mul_f32_e32 v28, v28, v26
	v_mul_f32_e32 v29, v29, v27
	v_mul_f32_e32 v30, v30, v28
	v_mul_f32_e32 v31, v31, v29
	v_cvt_pk_bf16_f32 v21, v30, v31
	v_lshlrev_b32_e32 v24, 16, v106
	v_and_b32_e32 v25, 0xffff0000, v106
	v_lshlrev_b32_e32 v26, 16, v110
	v_and_b32_e32 v27, 0xffff0000, v110
	v_add_f32_e32 v12, v12, v24
	v_add_f32_e32 v13, v13, v25
	v_mul_f32_e32 v28, 0xbfb8aa3b, v26
	v_mul_f32_e32 v29, 0xbfb8aa3b, v27
	v_exp_f32_e32 v28, v28
	v_exp_f32_e32 v29, v29
	v_fma_f32 v30, v18, v12, -v24
	v_fma_f32 v31, v18, v13, -v25
	v_add_f32_e32 v28, 1.0, v28
	v_add_f32_e32 v29, 1.0, v29
	v_rcp_f32_e32 v28, v28
	v_rcp_f32_e32 v29, v29
	v_mul_f32_e32 v30, v4, v30
	v_mul_f32_e32 v31, v5, v31
	v_mul_f32_e32 v28, v28, v26
	v_mul_f32_e32 v29, v29, v27
	v_mul_f32_e32 v30, v30, v28
	v_mul_f32_e32 v31, v31, v29
	v_cvt_pk_bf16_f32 v22, v30, v31
	v_lshlrev_b32_e32 v24, 16, v107
	v_and_b32_e32 v25, 0xffff0000, v107
	v_lshlrev_b32_e32 v26, 16, v111
	v_and_b32_e32 v27, 0xffff0000, v111
	v_add_f32_e32 v14, v14, v24
	v_add_f32_e32 v15, v15, v25
	v_mul_f32_e32 v28, 0xbfb8aa3b, v26
	v_mul_f32_e32 v29, 0xbfb8aa3b, v27
	v_exp_f32_e32 v28, v28
	v_exp_f32_e32 v29, v29
	v_fma_f32 v30, v18, v14, -v24
	v_fma_f32 v31, v18, v15, -v25
	v_add_f32_e32 v28, 1.0, v28
	v_add_f32_e32 v29, 1.0, v29
	v_rcp_f32_e32 v28, v28
	v_rcp_f32_e32 v29, v29
	v_mul_f32_e32 v30, v6, v30
	v_mul_f32_e32 v31, v7, v31
	v_mul_f32_e32 v28, v28, v26
	v_mul_f32_e32 v29, v29, v27
	v_mul_f32_e32 v30, v30, v28
	v_mul_f32_e32 v31, v31, v29
	v_cvt_pk_bf16_f32 v23, v30, v31
	global_store_dwordx4 v16, v[20:23], s[8:9]
	s_add_u32 s8, s8, 0x2000
	s_addc_u32 s9, s9, 0
	s_cmp_lt_u32 s23, s11
	s_cbranch_scc1 .Lpl_nolag_7
	v_lshlrev_b32_e32 v24, 16, v112
	v_and_b32_e32 v25, 0xffff0000, v112
	v_sub_f32_e32 v8, v8, v24
	v_sub_f32_e32 v9, v9, v25
	v_lshlrev_b32_e32 v24, 16, v113
	v_and_b32_e32 v25, 0xffff0000, v113
	v_sub_f32_e32 v10, v10, v24
	v_sub_f32_e32 v11, v11, v25
	v_lshlrev_b32_e32 v24, 16, v114
	v_and_b32_e32 v25, 0xffff0000, v114
	v_sub_f32_e32 v12, v12, v24
	v_sub_f32_e32 v13, v13, v25
	v_lshlrev_b32_e32 v24, 16, v115
	v_and_b32_e32 v25, 0xffff0000, v115
	v_sub_f32_e32 v14, v14, v24
	v_sub_f32_e32 v15, v15, v25
.Lpl_nolag_7:
	s_add_i32 s23, s23, 1
	s_cmp_eq_u32 s97, 1
	s_cbranch_scc1 .Lpl_wl_8
	s_waitcnt vmcnt(19)
	s_branch .Lpl_wj_8
.Lpl_wl_8:
	s_waitcnt vmcnt(7)

; __device__ __forceinline__ unsigned cvt_pk_bf16(float lo, float hi) { unsigned r; asm volatile("v_cvt_pk_bf16_f32 %0, %1, %2" : "=v"(r) : "v"(lo), "v"(hi)); return r; }
; __device__ __forceinline__ float silu_f(float v) { return v * __builtin_amdgcn_rcpf(1.f + __expf(-v)); }
; __device__ __forceinline__ void unpack8(const u32x4 w, float (&f)[8]) { f[0] = bf_lo(w.x); f[1] = bf_hi(w.x); f[2] = bf_lo(w.y); f[3] = bf_hi(w.y); f[4] = bf_lo(w.z); f[5] = bf_hi(w.z); f[6] = bf_lo(w.w); f[7] = bf_hi(w.w); }
; __device__ __forceinline__ void p3_pool(const Params& p) {
;     ...
;     for (int item = blockIdx.x; item < 256; item += gridDim.x) {
;         const int t0 = item * 64 + sub * 32, pos0 = t0 & (SEQ - 1);
;         float sum[8];
; #pragma unroll
;         for (int j = 0; j < 8; ++j) sum[j] = 0.f;
;         for (int i = 1; i < w; ++i) if (pos0 - i >= 0) { float f[8]; unpack8(*(const u32x4*)(proj + (size_t)(t0 - i) * NP2 + P2_U + j0), f);
; #pragma unroll
;             for (int j = 0; j < 8; ++j) sum[j] += f[j]; }
; #pragma unroll 4
;         for (int tt = 0; tt < 32; ++tt) {
;             const int t = t0 + tt, pos = pos0 + tt;
;             float u[8], gp[8];
;             unpack8(*(const u32x4*)(proj + (size_t)t * NP2 + P2_U + j0), u);
;             unpack8(*(const u32x4*)(proj + (size_t)t * NP2 + P2_GP + j0), gp);
;             const float icnt = 1.f / (float)min(pos + 1, w);
;             float y[8];
; #pragma unroll
;             for (int j = 0; j < 8; ++j) { sum[j] += u[j]; y[j] = (sum[j] * icnt - u[j]) * ps[j] * silu_f(gp[j]); }
;             u32x4 o; o.x = cvt_pk_bf16(y[0], y[1]); o.y = cvt_pk_bf16(y[2], y[3]); o.z = cvt_pk_bf16(y[4], y[5]); o.w = cvt_pk_bf16(y[6], y[7]);
;             *(u32x4*)(ycat + (size_t)t * DM + 2048 + j0) = o;
;             if (pos - (w - 1) >= 0) { float f[8]; unpack8(*(const u32x4*)(proj + (size_t)(t - (w - 1)) * NP2 + P2_U + j0), f);
; #pragma unroll
;                 for (int j = 0; j < 8; ++j) sum[j] -= f[j]; }
.Lpl_join_8:
	v_lshlrev_b32_e32 v24, 16, v116
	v_and_b32_e32 v25, 0xffff0000, v116
	v_lshlrev_b32_e32 v26, 16, v120
	v_and_b32_e32 v27, 0xffff0000, v120
	v_add_f32_e32 v8, v8, v24
	v_add_f32_e32 v9, v9, v25
	v_mul_f32_e32 v28, 0xbfb8aa3b, v26
	v_mul_f32_e32 v29, 0xbfb8aa3b, v27
	v_exp_f32_e32 v28, v28
	v_exp_f32_e32 v29, v29
	v_fma_f32 v30, v18, v8, -v24
	v_fma_f32 v31, v18, v9, -v25
	v_add_f32_e32 v28, 1.0, v28
	v_add_f32_e32 v29, 1.0, v29
	v_rcp_f32_e32 v28, v28
	v_rcp_f32_e32 v29, v29
	v_mul_f32_e32 v30, v0, v30
	v_mul_f32_e32 v31, v1, v31
	v_mul_f32_e32 v28, v28, v26
	v_mul_f32_e32 v29, v29, v27
	v_mul_f32_e32 v30, v30, v28
	v_mul_f32_e32 v31, v31, v29
	v_cvt_pk_bf16_f32 v20, v30, v31
	v_lshlrev_b32_e32 v24, 16, v117
	v_and_b32_e32 v25, 0xffff0000, v117
	v_lshlrev_b32_e32 v26, 16, v121
	v_and_b32_e32 v27, 0xffff0000, v121
	v_add_f32_e32 v10, v10, v24
	v_add_f32_e32 v11, v11, v25
	v_mul_f32_e32 v28, 0xbfb8aa3b, v26
	v_mul_f32_e32 v29, 0xbfb8aa3b, v27
	v_exp_f32_e32 v28, v28
	v_exp_f32_e32 v29, v29
	v_fma_f32 v30, v18, v10, -v24
	v_fma_f32 v31, v18, v11, -v25
	v_add_f32_e32 v28, 1.0, v28
	v_add_f32_e32 v29, 1.0, v29
	v_rcp_f32_e32 v28, v28
	v_rcp_f32_e32 v29, v29
	v_mul_f32_e32 v30, v2, v30
	v_mul_f32_e32 v31, v3, v31
	v_mul_f32_e32 v28, v28, v26
	v_mul_f32_e32 v29, v29, v27
	v_mul_f32_e32 v30, v30, v28
	v_mul_f32_e32 v31, v31, v29
	v_cvt_pk_bf16_f32 v21, v30, v31
	v_lshlrev_b32_e32 v24, 16, v118
	v_and_b32_e32 v25, 0xffff0000, v118
	v_lshlrev_b32_e32 v26, 16, v122
	v_and_b32_e32 v27, 0xffff0000, v122
	v_add_f32_e32 v12, v12, v24
	v_add_f32_e32 v13, v13, v25
	v_mul_f32_e32 v28, 0xbfb8aa3b, v26
	v_mul_f32_e32 v29, 0xbfb8aa3b, v27
	v_exp_f32_e32 v28, v28
	v_exp_f32_e32 v29, v29
	v_fma_f32 v30, v18, v12, -v24
	v_fma_f32 v31, v18, v13, -v25
	v_add_f32_e32 v28, 1.0, v28
	v_add_f32_e32 v29, 1.0, v29
	v_rcp_f32_e32 v28, v28
	v_rcp_f32_e32 v29, v29
	v_mul_f32_e32 v30, v4, v30
	v_mul_f32_e32 v31, v5, v31
	v_mul_f32_e32 v28, v28, v26
	v_mul_f32_e32 v29, v29, v27
	v_mul_f32_e32 v30, v30, v28
	v_mul_f32_e32 v31, v31, v29
	v_cvt_pk_bf16_f32 v22, v30, v31
	v_lshlrev_b32_e32 v24, 16, v119
	v_and_b32_e32 v25, 0xffff0000, v119
	v_lshlrev_b32_e32 v26, 16, v123
	v_and_b32_e32 v27, 0xffff0000, v123
	v_add_f32_e32 v14, v14, v24
	v_add_f32_e32 v15, v15, v25
	v_mul_f32_e32 v28, 0xbfb8aa3b, v26
	v_mul_f32_e32 v29, 0xbfb8aa3b, v27
	v_exp_f32_e32 v28, v28
	v_exp_f32_e32 v29, v29
	v_fma_f32 v30, v18, v14, -v24
	v_fma_f32 v31, v18, v15, -v25
	v_add_f32_e32 v28, 1.0, v28
	v_add_f32_e32 v29, 1.0, v29
	v_rcp_f32_e32 v28, v28
	v_rcp_f32_e32 v29, v29
	v_mul_f32_e32 v30, v6, v30
	v_mul_f32_e32 v31, v7, v31
	v_mul_f32_e32 v28, v28, v26
	v_mul_f32_e32 v29, v29, v27
	v_mul_f32_e32 v30, v30, v28
	v_mul_f32_e32 v31, v31, v29
	v_cvt_pk_bf16_f32 v23, v30, v31
	global_store_dwordx4 v16, v[20:23], s[8:9]
	s_add_u32 s8, s8, 0x2000
	s_addc_u32 s9, s9, 0
	s_cmp_lt_u32 s23, s11
	s_cbranch_scc1 .Lpl_nolag_8
	v_lshlrev_b32_e32 v24, 16, v124
	v_and_b32_e32 v25, 0xffff0000, v124
	v_sub_f32_e32 v8, v8, v24
	v_sub_f32_e32 v9, v9, v25
	v_lshlrev_b32_e32 v24, 16, v125
	v_and_b32_e32 v25, 0xffff0000, v125
	v_sub_f32_e32 v10, v10, v24
	v_sub_f32_e32 v11, v11, v25
	v_lshlrev_b32_e32 v24, 16, v126
	v_and_b32_e32 v25, 0xffff0000, v126
	v_sub_f32_e32 v12, v12, v24
	v_sub_f32_e32 v13, v13, v25
	v_lshlrev_b32_e32 v24, 16, v127
	v_and_b32_e32 v25, 0xffff0000, v127
	v_sub_f32_e32 v14, v14, v24
	v_sub_f32_e32 v15, v15, v25
.Lpl_nolag_8:
	s_add_i32 s23, s23, 1
	s_add_i32 s13, s13, 1
	s_cmp_lt_u32 s13, 4
	s_cbranch_scc1 .Lpl_pair
	s_add_i32 s12, s12, s34
	s_cmpk_gt_i32 s12, 0xff
	s_cbranch_scc0 .Lpl_item
	v_and_b32_e32 v34, 0x7f8, v172
	v_mov_b32_e32 v9, 0

; __device__ __forceinline__ unsigned cvt_pk_bf16(float lo, float hi) { unsigned r; asm volatile("v_cvt_pk_bf16_f32 %0, %1, %2" : "=v"(r) : "v"(lo), "v"(hi)); return r; }
; __device__ __forceinline__ float silu_f(float v) { return v * __builtin_amdgcn_rcpf(1.f + __expf(-v)); }
; __device__ __forceinline__ void unpack8(const u32x4 w, float (&f)[8]) { f[0] = bf_lo(w.x); f[1] = bf_hi(w.x); f[2] = bf_lo(w.y); f[3] = bf_hi(w.y); f[4] = bf_lo(w.z); f[5] = bf_hi(w.z); f[6] = bf_lo(w.w); f[7] = bf_hi(w.w); }
; __device__ __forceinline__ void p3_combine(const Params& p) {
;     ...
;     for (int t = blockIdx.x * 2 + sub; t < MTOK; t += gridDim.x * 2) {
;         float mp[3], lp[3];
; #pragma unroll
;         for (int q = 0; q < 3; ++q) { const float* mq = ml + ((size_t)q * MTOK + t) * 32 + h * 2; mp[q] = mq[0]; lp[q] = mq[1]; }
;         const float mm = fmaxf(mp[0], fmaxf(mp[1], mp[2]));
;         float num[8], den = 0.f;
; #pragma unroll
;         for (int j = 0; j < 8; ++j) num[j] = 0.f;
; #pragma unroll
;         for (int q = 0; q < 3; ++q) { const float wq = __builtin_amdgcn_exp2f(mp[q] - mm); den += wq * lp[q];
;             float f[8]; unpack8(*(const u32x4*)(ob + ((size_t)q * MTOK + t) * 2048 + j0), f);
; #pragma unroll
;             for (int j = 0; j < 8; ++j) num[j] += wq * f[j]; }
;         const float inv = 1.f / den;
;         float ga[8]; unpack8(*(const u32x4*)(proj2 + (size_t)t * NP2 + P2_GA + j0), ga);
;         float y[8];
; #pragma unroll
;         for (int j = 0; j < 8; ++j) y[j] = num[j] * inv * silu_f(ga[j]);
;         u32x4 o; o.x = cvt_pk_bf16(y[0], y[1]); o.y = cvt_pk_bf16(y[2], y[3]); o.z = cvt_pk_bf16(y[4], y[5]); o.w = cvt_pk_bf16(y[6], y[7]);
;         *(u32x4*)(ycat + (size_t)t * DM + j0) = o;
.LBB0_389:
	v_ashrrev_i32_e32 v1, 31, v0
	v_lshlrev_b64 v[10:11], 7, v[0:1]
	v_lshl_add_u64 v[22:23], v[2:3], 0, v[10:11]
	v_lshlrev_b64 v[10:11], 12, v[0:1]
	v_lshl_add_u64 v[14:15], v[4:5], 0, v[10:11]
	v_add_co_u32_e32 v24, vcc, s9, v14
	global_load_dwordx4 v[10:13], v[14:15], off
	s_nop 0
	v_addc_co_u32_e32 v25, vcc, 0, v15, vcc
	v_add_co_u32_e32 v26, vcc, s10, v14
	s_waitcnt vmcnt(0)
	v_lshlrev_b32_e32 v40, 16, v11
	v_addc_co_u32_e32 v27, vcc, 0, v15, vcc
	global_load_dwordx4 v[14:17], v[26:27], off
	global_load_dwordx4 v[18:21], v[24:25], off
	v_add_co_u32_e32 v24, vcc, 0x200000, v22
	v_and_b32_e32 v41, 0xffff0000, v11
	s_nop 0
	v_addc_co_u32_e32 v25, vcc, 0, v23, vcc
	v_add_co_u32_e32 v26, vcc, 0x400000, v22
	v_lshlrev_b32_e32 v44, 16, v13
	s_nop 0
	v_addc_co_u32_e32 v27, vcc, 0, v23, vcc
	global_load_dwordx2 v[28:29], v[22:23], off
	global_load_dwordx2 v[30:31], v[24:25], off
	global_load_dwordx2 v[32:33], v[26:27], off
	v_mad_i64_i32 v[22:23], s[20:21], v0, s11, v[6:7]
	global_load_dwordx4 v[22:25], v[22:23], off
	v_and_b32_e32 v45, 0xffff0000, v13
	v_lshlrev_b32_e32 v38, 16, v10
	v_and_b32_e32 v39, 0xffff0000, v10
	v_lshlrev_b32_e32 v42, 16, v12
	v_and_b32_e32 v43, 0xffff0000, v12
	s_waitcnt vmcnt(5)
	v_lshlrev_b32_e32 v11, 16, v14
	v_and_b32_e32 v13, 0xffff0000, v14
	s_waitcnt vmcnt(4)
	v_lshlrev_b32_e32 v26, 16, v19
	v_and_b32_e32 v14, 0xffff0000, v19
	v_lshlrev_b32_e32 v19, 16, v16
	v_and_b32_e32 v35, 0xffff0000, v16
	v_lshlrev_b32_e32 v10, 16, v18
	v_and_b32_e32 v12, 0xffff0000, v18
	v_lshlrev_b32_e32 v18, 16, v20
	v_and_b32_e32 v34, 0xffff0000, v20
	v_lshlrev_b32_e32 v37, 16, v17
	v_lshlrev_b32_e32 v36, 16, v21
	s_waitcnt vmcnt(1)
	v_max3_f32 v16, v28, v30, v32
	v_sub_f32_e32 v20, v28, v16
	v_sub_f32_e32 v28, v30, v16
	v_sub_f32_e32 v16, v32, v16
	v_exp_f32_e32 v20, v20
	v_mov_b32_e32 v30, v33
	v_exp_f32_e32 v33, v28
	v_exp_f32_e32 v32, v16
	v_fma_f32 v16, v20, v38, 0
	v_fma_f32 v38, v20, v39, 0
	v_fma_f32 v39, v20, v40, 0
	v_fma_f32 v40, v20, v41, 0
	v_fma_f32 v41, v20, v42, 0
	v_fma_f32 v42, v20, v43, 0
	v_fma_f32 v43, v20, v44, 0
	v_fma_f32 v44, v20, v45, 0
	v_fma_f32 v20, v29, v20, 0
	v_pk_mul_f32 v[28:29], v[30:31], v[32:33]
	v_mov_b32_e32 v30, v33
	v_mov_b32_e32 v31, v32
	v_add_f32_e32 v20, v29, v20
	v_pk_mul_f32 v[10:11], v[30:31], v[10:11]
	v_pk_mul_f32 v[32:33], v[30:31], v[34:35]
	v_pk_mul_f32 v[34:35], v[30:31], v[36:37]
	v_pk_mul_f32 v[12:13], v[30:31], v[12:13]
	v_add_f32_e32 v10, v16, v10
	v_add_f32_e32 v29, v42, v32
	v_add_f32_e32 v32, v43, v34
	v_add_f32_e32 v34, v28, v20
	v_add_f32_e32 v12, v38, v12
	v_add_f32_e32 v10, v10, v11
	v_div_scale_f32 v11, s[20:21], v34, v34, 1.0
	v_add_f32_e32 v12, v12, v13
	v_rcp_f32_e32 v13, v11
	v_lshlrev_b32_e32 v27, 16, v15
	v_and_b32_e32 v15, 0xffff0000, v15
	v_pk_mul_f32 v[26:27], v[30:31], v[26:27]
	v_pk_mul_f32 v[14:15], v[30:31], v[14:15]
	v_add_f32_e32 v16, v39, v26
	v_add_f32_e32 v26, v40, v14
	v_add_f32_e32 v14, v16, v27
	v_add_f32_e32 v16, v26, v15
	v_fma_f32 v15, -v11, v13, 1.0
	v_pk_mul_f32 v[18:19], v[30:31], v[18:19]
	v_fmac_f32_e32 v13, v15, v13
	v_div_scale_f32 v15, vcc, 1.0, v34, 1.0
	v_add_f32_e32 v18, v41, v18
	v_add_f32_e32 v20, v29, v33
	v_and_b32_e32 v29, 0xffff0000, v17
	v_mul_f32_e32 v17, v15, v13
	v_add_f32_e32 v18, v18, v19
	v_fma_f32 v19, -v11, v17, v15
	v_fmac_f32_e32 v17, v19, v13
	v_fma_f32 v15, -v11, v17, v15
	s_waitcnt vmcnt(0)
	v_lshlrev_b32_e32 v11, 16, v22
	v_mul_f32_e32 v19, 0xbfb8aa3b, v11
	v_exp_f32_e32 v19, v19
	v_div_fmas_f32 v15, v15, v13, v17
	v_and_b32_e32 v13, 0xffff0000, v22
	v_add_f32_e32 v26, v32, v35
	v_add_f32_e32 v17, 1.0, v19
	v_rcp_f32_e32 v33, v17
	v_mul_f32_e32 v17, 0xbfb8aa3b, v13
	v_exp_f32_e32 v17, v17
	v_div_fixup_f32 v32, v15, v34, 1.0
	v_lshlrev_b32_e32 v15, 16, v23
	v_pk_mul_f32 v[10:11], v[32:33], v[10:11]
	v_add_f32_e32 v17, 1.0, v17
	v_rcp_f32_e32 v33, v17
	v_mul_f32_e32 v17, 0xbfb8aa3b, v15
	v_exp_f32_e32 v19, v17
	v_and_b32_e32 v17, 0xffff0000, v23
	v_pk_mul_f32 v[12:13], v[32:33], v[12:13]
	v_and_b32_e32 v28, 0xffff0000, v21
	v_add_f32_e32 v19, 1.0, v19
	v_rcp_f32_e32 v33, v19
	v_mul_f32_e32 v19, 0xbfb8aa3b, v17
	v_exp_f32_e32 v21, v19
	v_lshlrev_b32_e32 v19, 16, v24
	v_pk_mul_f32 v[14:15], v[32:33], v[14:15]
	v_lshlrev_b32_e32 v27, 16, v25
	v_add_f32_e32 v21, 1.0, v21
	v_rcp_f32_e32 v33, v21
	v_mul_f32_e32 v21, 0xbfb8aa3b, v19
	v_exp_f32_e32 v23, v21
	v_and_b32_e32 v21, 0xffff0000, v24
	v_pk_mul_f32 v[16:17], v[32:33], v[16:17]
	v_pk_mul_f32 v[28:29], v[30:31], v[28:29]
	v_add_f32_e32 v23, 1.0, v23
	v_rcp_f32_e32 v33, v23
	v_mul_f32_e32 v23, 0xbfb8aa3b, v21
	v_exp_f32_e32 v24, v23
	v_add_f32_e32 v22, v44, v28
	v_pk_mul_f32 v[18:19], v[32:33], v[18:19]
	v_and_b32_e32 v23, 0xffff0000, v25
	v_add_f32_e32 v24, 1.0, v24
	v_rcp_f32_e32 v33, v24
	v_mul_f32_e32 v24, 0xbfb8aa3b, v27
	v_exp_f32_e32 v24, v24
	v_mul_f32_e32 v28, v12, v13
	v_mul_f32_e32 v25, v10, v11
	v_pk_mul_f32 v[10:11], v[32:33], v[20:21]
	v_add_f32_e32 v12, 1.0, v24
	v_rcp_f32_e32 v33, v12
	v_mul_f32_e32 v12, 0xbfb8aa3b, v23
	v_exp_f32_e32 v20, v12
	v_mul_f32_e32 v14, v14, v15
	v_mul_f32_e32 v15, v16, v17
	v_pk_mul_f32 v[12:13], v[32:33], v[26:27]
	v_add_f32_e32 v16, 1.0, v20
	v_rcp_f32_e32 v33, v16
	v_add_f32_e32 v22, v22, v29
	v_mul_f32_e32 v17, v10, v11
	v_mul_f32_e32 v16, v18, v19
	v_pk_mul_f32 v[10:11], v[32:33], v[22:23]
	v_mul_f32_e32 v13, v12, v13
	v_mul_f32_e32 v18, v10, v11
	v_cvt_pk_bf16_f32 v10, v25, v28
	v_cvt_pk_bf16_f32 v11, v14, v15
	v_lshlrev_b64 v[14:15], 13, v[0:1]
	v_add_u32_e32 v0, s8, v0
	v_cmp_lt_i32_e32 vcc, s12, v0
	v_lshl_add_u64 v[14:15], v[8:9], 0, v[14:15]
	s_or_b64 s[6:7], vcc, s[6:7]
	v_cvt_pk_bf16_f32 v12, v16, v17
	v_cvt_pk_bf16_f32 v13, v13, v18
	global_store_dwordx4 v[14:15], v[10:13], off
	s_andn2_b64 exec, exec, s[6:7]
	s_cbranch_execnz .LBB0_389

; __global__ void __launch_bounds__(NTHREADS, 2) fwd_megakernel(Params p) {
	.amdhsa_kernel _Z14fwd_megakernel6Params
		.amdhsa_group_segment_fixed_size 0
		.amdhsa_private_segment_fixed_size 0
		.amdhsa_kernarg_size 352
		.amdhsa_user_sgpr_count 2
		.amdhsa_user_sgpr_dispatch_ptr 0
		.amdhsa_user_sgpr_queue_ptr 0
		.amdhsa_user_sgpr_kernarg_segment_ptr 1
		.amdhsa_user_sgpr_dispatch_id 0
		.amdhsa_user_sgpr_kernarg_preload_length 0
		.amdhsa_user_sgpr_kernarg_preload_offset 0
		.amdhsa_user_sgpr_private_segment_size 0
		.amdhsa_uses_dynamic_stack 0
		.amdhsa_enable_private_segment 0
		.amdhsa_system_sgpr_workgroup_id_x 1
		.amdhsa_system_sgpr_workgroup_id_y 0
		.amdhsa_system_sgpr_workgroup_id_z 0
		.amdhsa_system_sgpr_workgroup_info 0
		.amdhsa_system_vgpr_workitem_id 2
		.amdhsa_next_free_vgpr 238
		.amdhsa_next_free_sgpr 102
		.amdhsa_accum_offset 240
		.amdhsa_reserve_vcc 1
		.amdhsa_float_round_mode_32 0
		.amdhsa_float_round_mode_16_64 0
		.amdhsa_float_denorm_mode_32 3
		.amdhsa_float_denorm_mode_16_64 3
		.amdhsa_dx10_clamp 1
		.amdhsa_ieee_mode 1
		.amdhsa_fp16_overflow 0
		.amdhsa_tg_split 0
		.amdhsa_exception_fp_ieee_invalid_op 0
		.amdhsa_exception_fp_denorm_src 0
		.amdhsa_exception_fp_ieee_div_zero 0
		.amdhsa_exception_fp_ieee_overflow 0
		.amdhsa_exception_fp_ieee_underflow 0
		.amdhsa_exception_fp_ieee_inexact 0
		.amdhsa_exception_int_div_zero 0
	.end_amdhsa_kernel

; __global__ void __launch_bounds__(NTHREADS, 2) fwd_megakernel(Params p) {
amdhsa.kernels:
  - .agpr_count:     0
    .args:
      - .offset:         0
        .size:           96
        .value_kind:     by_value
      - .offset:         96
        .size:           4
        .value_kind:     hidden_block_count_x
      - .offset:         100
        .size:           4
        .value_kind:     hidden_block_count_y
      - .offset:         104
        .size:           4
        .value_kind:     hidden_block_count_z
      - .offset:         108
        .size:           2
        .value_kind:     hidden_group_size_x
      - .offset:         110
        .size:           2
        .value_kind:     hidden_group_size_y
      - .offset:         112
        .size:           2
        .value_kind:     hidden_group_size_z
      - .offset:         114
        .size:           2
        .value_kind:     hidden_remainder_x
      - .offset:         116
        .size:           2
        .value_kind:     hidden_remainder_y
      - .offset:         118
        .size:           2
        .value_kind:     hidden_remainder_z
      - .offset:         136
        .size:           8
        .value_kind:     hidden_global_offset_x
      - .offset:         144
        .size:           8
        .value_kind:     hidden_global_offset_y
      - .offset:         152
        .size:           8
        .value_kind:     hidden_global_offset_z
      - .offset:         160
        .size:           2
        .value_kind:     hidden_grid_dims
      - .offset:         184
        .size:           8
        .value_kind:     hidden_multigrid_sync_arg
      - .offset:         216
        .size:           4
        .value_kind:     hidden_dynamic_lds_size
    .group_segment_fixed_size: 0
    .kernarg_segment_align: 8
    .kernarg_segment_size: 352
    .language:       OpenCL C
    .language_version:
      - 2
      - 0
    .max_flat_workgroup_size: 512
    .name:           _Z14fwd_megakernel6Params
    .private_segment_fixed_size: 0
    .sgpr_count:     108
    .sgpr_spill_count: 0
    .symbol:         _Z14fwd_megakernel6Params.kd
    .uniform_work_group_size: 1
    .uses_dynamic_stack: false
    .vgpr_count:     238
    .vgpr_spill_count: 0
    .wavefront_size: 64
